# adds ret_scan V-operand loads issued together (were 4 serialized round trips) and fast pipelined weight conversion on idle WGs of the latent scan
# baseline (speedup 1.0000x reference)
.LBB0_7:
	s_or_b64 exec, exec, s[4:5]
	s_load_dword s2, s[0:1], 0x40c
	v_mov_b32_e32 v2, v189
	s_waitcnt lgkmcnt(0)
	s_add_i32 s14, s2, 0x140
	s_cmp_ge_i32 s73, s14
	s_cbranch_scc1 .LBB0_57
	s_add_i32 s15, s2, 0xc0
	v_and_b32_e32 v3, 15, v2
	v_lshlrev_b32_e32 v4, 3, v3
	v_mov_b32_e32 v5, 0
	s_getpc_b64 s[4:5]
	s_add_u32 s4, s4, c_invf@rel32@lo+4
	s_addc_u32 s5, s5, c_invf@rel32@hi+12
	v_lshl_add_u64 v[6:7], s[4:5], 0, v[4:5]
	v_and_b32_e32 v4, 16, v2
	v_bfe_i32 v8, v2, 4, 1
	s_movk_i32 s18, 0xb00
	v_cmp_eq_u32_e64 s[4:5], 0, v4
	v_and_b32_e32 v52, 63, v2
	v_and_or_b32 v53, v8, s18, v3
	v_lshlrev_b32_e32 v4, 6, v2
	s_movk_i32 s18, 0x400
	v_ashrrev_i32_e32 v55, 3, v2
	v_lshlrev_b32_e32 v12, 3, v2
	v_and_or_b32 v3, v4, s18, v3
	v_and_b32_e32 v56, -8, v55
	v_lshlrev_b32_e32 v4, 2, v52
	s_movk_i32 s20, 0x104
	v_or_b32_e32 v68, 7, v55
	v_mad_u64_u32 v[8:9], s[18:19], v56, s20, v[4:5]
	v_mad_u64_u32 v[10:11], s[18:19], v68, s20, v[4:5]
	v_and_b32_e32 v4, 56, v12
	v_ashrrev_i32_e32 v20, 6, v2
	s_add_u32 s24, s16, 0x80000
	v_add_u32_e32 v54, 0x400, v3
	v_mul_u32_u24_e32 v3, 0x41, v4
	v_and_b32_e32 v69, 0x7f, v2
	s_addc_u32 s25, s17, 0
	v_lshlrev_b32_e32 v18, 7, v20
	v_and_b32_e32 v21, 0x1f8, v12
	v_lshlrev_b32_e32 v3, 2, v3
	s_movk_i32 s18, 0xa00
	v_lshlrev_b32_e32 v12, 2, v69
	v_mov_b32_e32 v13, v5
	s_movk_i32 s21, 0x6000
	s_movk_i32 s6, 0x1400
	s_movk_i32 s8, 0x280
	v_lshl_add_u32 v11, v55, 2, v3
	v_mul_lo_u32 v22, v20, s18
	v_lshl_add_u64 v[14:15], s[16:17], 0, v[12:13]
	v_ashrrev_i32_e32 v3, 31, v2
	v_mad_i64_i32 v[18:19], s[16:17], v18, s21, 0
	s_add_u32 s26, s0, 0x400
	s_mov_b32 s28, 0x6dc9c883
	s_mov_b32 s30, 0x54442d18
	s_mov_b32 s34, 0x13a86d09
	s_mov_b32 s36, 0xeff8d898
	v_add_u32_e32 v1, 0xfffe8000, v2
	v_cmp_gt_i32_e64 s[6:7], s6, v2
	v_cmp_gt_i32_e64 s[8:9], s8, v2
	v_or_b32_e32 v9, 1, v56
	v_add_u32_e32 v57, 0x104, v8
	v_or_b32_e32 v58, 2, v56
	v_add_u32_e32 v59, 0x208, v8
	v_or_b32_e32 v60, 3, v56
	v_add_u32_e32 v61, 0x30c, v8
	v_or_b32_e32 v62, 4, v56
	v_add_u32_e32 v63, 0x410, v8
	v_or_b32_e32 v64, 5, v56
	v_add_u32_e32 v65, 0x514, v8
	v_or_b32_e32 v66, 6, v56
	v_add_u32_e32 v67, 0x618, v8
	s_movk_i32 s20, 0x7f
	v_lshlrev_b64 v[16:17], 2, v[2:3]
	v_lshlrev_b32_e32 v3, 2, v2
	v_lshl_or_b32 v18, v52, 3, v18
	v_lshlrev_b32_e32 v13, 9, v20
	s_addc_u32 s27, s1, 0
	s_mov_b32 s29, 0x3fe45f30
	s_mov_b32 s31, 0xbff921fb
	s_mov_b32 s35, 0x3de61246
	s_mov_b32 s37, 0x3e21eed8
	s_movk_i32 s33, 0xfff
	s_movk_i32 s46, 0x3ff
	s_mov_b64 s[38:39], 0x800
	s_movk_i32 s47, 0x11ff
	s_mov_b32 s48, 0xc000
	s_mov_b32 s49, 0x12000
	v_add_u32_e32 v70, v21, v22
	v_lshlrev_b32_e32 v20, 1, v4
	v_mov_b32_e32 v22, 0x67f544e4
	v_mov_b32_e32 v23, 0xbe5ae645
	v_mov_b32_e32 v24, 0xa556c734
	v_mov_b32_e32 v25, 0x3ec71de3
	v_mov_b32_e32 v26, 0x1a01a01a
	v_mov_b32_e32 v27, 0xbf2a01a0
	v_mov_b32_e32 v28, 0x11111111
	v_mov_b32_e32 v29, 0x3f811111
	v_mov_b32_e32 v30, 0x55555555
	v_mov_b32_e32 v31, 0xbfc55555
	v_mov_b32_e32 v32, 0xb7789f5c
	v_mov_b32_e32 v33, 0xbe927e4f
	v_mov_b32_e32 v35, 0x3efa01a0
	v_mov_b32_e32 v36, 0x16c16c17
	v_mov_b32_e32 v37, 0xbf56c16c
	v_mov_b32_e32 v39, 0x3fa55555
	v_add_u32_e32 v71, 0x400, v11
	v_and_b32_e32 v114, 63, v189
	v_lshrrev_b32_e32 v115, 3, v189
	v_and_b32_e32 v115, 56, v115
	v_mul_u32_u24_e32 v116, 0x41, v115
	v_add_lshl_u32 v116, v116, v114, 2
	v_lshrrev_b32_e32 v117, 3, v189
	v_and_b32_e32 v118, 7, v189
	v_lshlrev_b32_e32 v118, 3, v118
	v_mul_u32_u24_e32 v119, 0x41, v118
	v_add_lshl_u32 v119, v119, v117, 2
	v_add_u32_e32 v131, 0x410, v119
	v_add_u32_e32 v143, 0x4100, v119
	v_add_u32_e32 v155, 0x4510, v119
	v_mul_u32_u24_e32 v168, 40, v114
	v_add_u32_e32 v168, 0xe8, v168
	v_bfrev_b32_e32 v106, -2
	v_cmp_gt_u32_e64 s[88:89], 20, v114
	s_nop 1
	s_and_saveexec_b64 s[90:91], s[88:89]
	global_load_dword v106, v168, s[0:1] offset:32
	global_load_dword v107, v168, s[0:1] offset:0
	global_load_dword v108, v168, s[0:1] offset:4
	global_load_dword v109, v168, s[0:1] offset:8
	global_load_dword v110, v168, s[0:1] offset:12
	global_load_dword v111, v168, s[0:1] offset:16
	global_load_dword v112, v168, s[0:1] offset:20
	global_load_dword v113, v168, s[0:1] offset:28
	s_mov_b64 exec, s[90:91]
	s_waitcnt vmcnt(0)
	s_mov_b32 s68, s73
	s_mov_b32 s69, s73
	s_mul_i32 s72, s3, 3
	s_cmp_ge_i32 s68, s2
	s_cbranch_scc1 .Lcv_pro_done
	v_cmp_le_i32_e64 s[88:89], v106, s68
	s_nop 1
	s_bcnt1_i32_b64 s74, s[88:89]
	s_sub_u32 s74, s74, 1
	s_nop 3
	v_readlane_b32 s67, v106, s74
	v_readlane_b32 s60, v107, s74
	v_readlane_b32 s61, v108, s74
	v_readlane_b32 s62, v109, s74
	v_readlane_b32 s63, v110, s74
	v_readlane_b32 s64, v111, s74
	v_readlane_b32 s65, v112, s74
	v_readlane_b32 s66, v113, s74
	s_nop 3
	s_sub_u32 s75, s68, s67
	s_lshr_b32 s90, s64, 6
	s_mov_b32 s91, 0x10000000
	s_cmp_eq_u32 s90, 6
	s_cselect_b32 s91, 0x2aaaaaab, s91
	s_cmp_eq_u32 s90, 4
	s_cselect_b32 s91, 0x40000000, s91
	s_cmp_eq_u32 s90, 44
	s_cselect_b32 s91, 0x5d1745e, s91
	s_cmp_eq_u32 s90, 32
	s_cselect_b32 s91, 0x8000000, s91
	s_mul_hi_u32 s92, s75, s91
	s_mul_i32 s93, s92, s90
	s_sub_u32 s93, s75, s93
	s_lshl_b32 s92, s92, 6
	s_lshl_b32 s93, s93, 6
	s_cmp_lt_u32 s92, s65
	s_cselect_b32 s94, -1, 0
	s_cselect_b32 s95, s92, 0
	v_add_u32_e32 v168, s92, v117
	v_mul_lo_u32 v168, v168, s64
	v_add3_u32 v168, v168, v118, s93
	v_lshlrev_b32_e32 v168, 1, v168
	v_mov_b32_e32 v169, 0
	v_lshl_add_u64 v[128:129], v[168:169], 0, s[62:63]
	v_mov_b32_e32 v130, s94
	v_add_u32_e32 v168, s95, v114
	s_cmp_eq_u32 s66, 0
	s_cbranch_scc1 .Lcv_sc_done_p0
	s_cmp_eq_u32 s66, 2
	s_cbranch_scc1 .Lcv_sc_m2_p0
	s_cmpk_lt_u32 s95, 0x400
	s_cbranch_scc1 .Lcv_sc_done_p0
	v_add_u32_e32 v168, 0xfffffc00, v168
	v_lshrrev_b32_e32 v169, 5, v168
	v_lshlrev_b32_e32 v169, 4, v169
	v_and_b32_e32 v170, 15, v168
	v_bfe_u32 v171, v168, 4, 1
	v_lshlrev_b32_e32 v171, 10, v171
	v_add3_u32 v168, v169, v170, v171
	v_add_u32_e32 v168, 0x400, v168
	s_branch .Lcv_sc_done_p0

.LBB0_296:
	s_or_b64 exec, exec, s[4:5]
	v_cmp_ne_u32_e32 vcc, 0, v0
	v_cmp_le_i32_e64 s[4:5], s10, v2
	s_mov_b64 s[54:55], exec
	v_readlane_b32 s6, v255, 26
	v_readlane_b32 s7, v255, 27
	s_and_b64 s[6:7], s[54:55], s[6:7]
	s_mov_b64 exec, s[6:7]
	s_cbranch_execz .LBB0_319
	v_writelane_b32 v250, s68, 0
	v_writelane_b32 v250, s69, 1
	v_writelane_b32 v250, s70, 2
	v_writelane_b32 v250, s71, 3
	v_writelane_b32 v250, s72, 4
	v_writelane_b32 v250, s74, 5
	v_writelane_b32 v250, s75, 6
	v_writelane_b32 v250, s76, 7
	v_writelane_b32 v250, s77, 8
	v_writelane_b32 v250, s78, 9
	v_writelane_b32 v250, s79, 10
	v_writelane_b32 v250, s80, 11
	v_writelane_b32 v250, s81, 12
	v_writelane_b32 v250, s82, 13
	v_writelane_b32 v250, s83, 14
	v_writelane_b32 v250, s84, 15
	v_writelane_b32 v250, s85, 16
	v_writelane_b32 v250, s86, 17
	v_writelane_b32 v250, s87, 18
	v_writelane_b32 v250, s88, 19
	v_writelane_b32 v250, s89, 20
	v_writelane_b32 v250, s90, 21
	v_writelane_b32 v250, s91, 22
	v_writelane_b32 v250, s92, 23
	v_writelane_b32 v250, s93, 24
	v_writelane_b32 v250, s94, 25
	v_writelane_b32 v250, s95, 26
	v_writelane_b32 v250, s96, 27
	v_writelane_b32 v250, s97, 28
	s_load_dwordx2 s[70:71], s[0:1], 0x408
	s_waitcnt lgkmcnt(0)
	s_lshr_b32 s69, s73, 1
	s_add_u32 s69, s69, s71
	s_mov_b32 s71, s70
	s_lshr_b32 s70, s3, 1
	v_and_b32_e32 v50, 63, v189
	v_lshrrev_b32_e32 v51, 3, v189
	v_and_b32_e32 v51, 56, v51
	v_mul_u32_u24_e32 v52, 0x41, v51
	v_add_lshl_u32 v52, v52, v50, 2
	v_lshrrev_b32_e32 v53, 3, v189
	v_and_b32_e32 v54, 7, v189
	v_lshlrev_b32_e32 v54, 3, v54
	v_mul_u32_u24_e32 v55, 0x41, v54
	v_add_lshl_u32 v55, v55, v53, 2
	v_add_u32_e32 v67, 0x410, v55
	v_add_u32_e32 v79, 0x4100, v55
	v_add_u32_e32 v91, 0x4510, v55
	v_mul_u32_u24_e32 v104, 40, v50
	v_add_u32_e32 v104, 0xe8, v104
	v_bfrev_b32_e32 v42, -2
	v_cmp_gt_u32_e64 s[88:89], 20, v50
	s_nop 1
	s_and_saveexec_b64 s[90:91], s[88:89]
	global_load_dword v42, v104, s[0:1] offset:32
	global_load_dword v43, v104, s[0:1] offset:0
	global_load_dword v44, v104, s[0:1] offset:4
	global_load_dword v45, v104, s[0:1] offset:8
	global_load_dword v46, v104, s[0:1] offset:12
	global_load_dword v47, v104, s[0:1] offset:16
	global_load_dword v48, v104, s[0:1] offset:20
	global_load_dword v49, v104, s[0:1] offset:28
	s_mov_b64 exec, s[90:91]
	s_waitcnt vmcnt(0)
	s_mov_b32 s84, s69
	s_mov_b32 s85, s69
	s_mul_i32 s86, s70, 3
	s_cmp_ge_i32 s84, s71
	s_cbranch_scc1 .Lcvs_pro_done
	v_cmp_le_i32_e64 s[88:89], v42, s84
	s_nop 1
	s_bcnt1_i32_b64 s87, s[88:89]
	s_sub_u32 s87, s87, 1
	s_nop 3
	v_readlane_b32 s83, v42, s87
	v_readlane_b32 s76, v43, s87
	v_readlane_b32 s77, v44, s87
	v_readlane_b32 s78, v45, s87
	v_readlane_b32 s79, v46, s87
	v_readlane_b32 s80, v47, s87
	v_readlane_b32 s81, v48, s87
	v_readlane_b32 s82, v49, s87
	s_nop 3
	s_sub_u32 s92, s84, s83
	s_lshr_b32 s93, s80, 6
	s_mov_b32 s94, 0x10000000
	s_cmp_eq_u32 s93, 6
	s_cselect_b32 s94, 0x2aaaaaab, s94
	s_cmp_eq_u32 s93, 4
	s_cselect_b32 s94, 0x40000000, s94
	s_cmp_eq_u32 s93, 44
	s_cselect_b32 s94, 0x5d1745e, s94
	s_cmp_eq_u32 s93, 32
	s_cselect_b32 s94, 0x8000000, s94
	s_mul_hi_u32 s95, s92, s94
	s_mul_i32 s96, s95, s93
	s_sub_u32 s96, s92, s96
	s_lshl_b32 s95, s95, 6
	s_lshl_b32 s96, s96, 6
	s_cmp_lt_u32 s95, s81
	s_cselect_b32 s97, -1, 0
	s_cselect_b32 s74, s95, 0
	v_add_u32_e32 v104, s95, v53
	v_mul_lo_u32 v104, v104, s80
	v_add3_u32 v104, v104, v54, s96
	v_lshlrev_b32_e32 v104, 1, v104
	v_mov_b32_e32 v105, 0
	v_lshl_add_u64 v[64:65], v[104:105], 0, s[78:79]
	v_mov_b32_e32 v66, s97
	v_add_u32_e32 v104, s74, v50
	s_cmp_eq_u32 s82, 0
	s_cbranch_scc1 .Lcvs_sc_done_p0
	s_cmp_eq_u32 s82, 2
	s_cbranch_scc1 .Lcvs_sc_m2_p0
	s_cmpk_lt_u32 s74, 0x400
	s_cbranch_scc1 .Lcvs_sc_done_p0
	v_add_u32_e32 v104, 0xfffffc00, v104
	v_lshrrev_b32_e32 v105, 5, v104
	v_lshlrev_b32_e32 v105, 4, v105
	v_and_b32_e32 v106, 15, v104
	v_bfe_u32 v107, v104, 4, 1
	v_lshlrev_b32_e32 v107, 10, v107
	v_add3_u32 v104, v105, v106, v107
	v_add_u32_e32 v104, 0x400, v104
	s_branch .Lcvs_sc_done_p0
.Lcvs_sc_m2_p0:
	v_lshrrev_b32_e32 v105, 5, v104
	v_lshlrev_b32_e32 v105, 4, v105
	v_and_b32_e32 v106, 15, v104
	v_bfe_u32 v107, v104, 4, 1
	v_mul_u32_u24_e32 v107, 0xb00, v107
	v_add3_u32 v104, v105, v106, v107
.Lcvs_sc_done_p0:
	v_add_u32_e32 v105, s96, v51
	v_mul_lo_u32 v105, v105, s81
	v_add_lshl_u32 v56, v105, v104, 2
	s_lshl_b32 s75, s81, 2
	v_add_u32_e32 v57, s75, v56
	v_add_u32_e32 v58, s75, v57
	v_add_u32_e32 v59, s75, v58
	v_add_u32_e32 v60, s75, v59
	v_add_u32_e32 v61, s75, v60
	v_add_u32_e32 v62, s75, v61
	v_add_u32_e32 v63, s75, v62
	global_load_dword v56, v56, s[76:77]
	global_load_dword v57, v57, s[76:77]
	global_load_dword v58, v58, s[76:77]
	global_load_dword v59, v59, s[76:77]
	global_load_dword v60, v60, s[76:77]
	global_load_dword v61, v61, s[76:77]
	global_load_dword v62, v62, s[76:77]
	global_load_dword v63, v63, s[76:77]
	s_add_i32 s84, s84, s70
	s_cmp_ge_i32 s84, s71
	s_cbranch_scc1 .Lcvs_pro_done
	v_cmp_le_i32_e64 s[88:89], v42, s84
	s_nop 1
	s_bcnt1_i32_b64 s87, s[88:89]
	s_sub_u32 s87, s87, 1
	s_nop 3
	v_readlane_b32 s83, v42, s87
	v_readlane_b32 s76, v43, s87
	v_readlane_b32 s77, v44, s87
	v_readlane_b32 s78, v45, s87
	v_readlane_b32 s79, v46, s87
	v_readlane_b32 s80, v47, s87
	v_readlane_b32 s81, v48, s87
	v_readlane_b32 s82, v49, s87
	s_nop 3
	s_sub_u32 s92, s84, s83
	s_lshr_b32 s93, s80, 6
	s_mov_b32 s94, 0x10000000
	s_cmp_eq_u32 s93, 6
	s_cselect_b32 s94, 0x2aaaaaab, s94
	s_cmp_eq_u32 s93, 4
	s_cselect_b32 s94, 0x40000000, s94
	s_cmp_eq_u32 s93, 44
	s_cselect_b32 s94, 0x5d1745e, s94
	s_cmp_eq_u32 s93, 32
	s_cselect_b32 s94, 0x8000000, s94
	s_mul_hi_u32 s95, s92, s94
	s_mul_i32 s96, s95, s93
	s_sub_u32 s96, s92, s96
	s_lshl_b32 s95, s95, 6
	s_lshl_b32 s96, s96, 6
	s_cmp_lt_u32 s95, s81
	s_cselect_b32 s97, -1, 0
	s_cselect_b32 s74, s95, 0
	v_add_u32_e32 v104, s95, v53
	v_mul_lo_u32 v104, v104, s80
	v_add3_u32 v104, v104, v54, s96
	v_lshlrev_b32_e32 v104, 1, v104
	v_mov_b32_e32 v105, 0
	v_lshl_add_u64 v[76:77], v[104:105], 0, s[78:79]
	v_mov_b32_e32 v78, s97
	v_add_u32_e32 v104, s74, v50
	s_cmp_eq_u32 s82, 0
	s_cbranch_scc1 .Lcvs_sc_done_p1
	s_cmp_eq_u32 s82, 2
	s_cbranch_scc1 .Lcvs_sc_m2_p1
	s_cmpk_lt_u32 s74, 0x400
	s_cbranch_scc1 .Lcvs_sc_done_p1
	v_add_u32_e32 v104, 0xfffffc00, v104
	v_lshrrev_b32_e32 v105, 5, v104
	v_lshlrev_b32_e32 v105, 4, v105
	v_and_b32_e32 v106, 15, v104
	v_bfe_u32 v107, v104, 4, 1
	v_lshlrev_b32_e32 v107, 10, v107
	v_add3_u32 v104, v105, v106, v107
	v_add_u32_e32 v104, 0x400, v104
	s_branch .Lcvs_sc_done_p1

.Lcvs_sc_done_p1:
	v_add_u32_e32 v105, s96, v51
	v_mul_lo_u32 v105, v105, s81
	v_add_lshl_u32 v68, v105, v104, 2
	s_lshl_b32 s75, s81, 2
	v_add_u32_e32 v69, s75, v68
	v_add_u32_e32 v70, s75, v69
	v_add_u32_e32 v71, s75, v70
	v_add_u32_e32 v72, s75, v71
	v_add_u32_e32 v73, s75, v72
	v_add_u32_e32 v74, s75, v73
	v_add_u32_e32 v75, s75, v74
	global_load_dword v68, v68, s[76:77]
	global_load_dword v69, v69, s[76:77]
	global_load_dword v70, v70, s[76:77]
	global_load_dword v71, v71, s[76:77]
	global_load_dword v72, v72, s[76:77]
	global_load_dword v73, v73, s[76:77]
	global_load_dword v74, v74, s[76:77]
	global_load_dword v75, v75, s[76:77]
	s_add_i32 s84, s84, s70
	s_cmp_ge_i32 s84, s71
	s_cbranch_scc1 .Lcvs_pro_done
	v_cmp_le_i32_e64 s[88:89], v42, s84
	s_nop 1
	s_bcnt1_i32_b64 s87, s[88:89]
	s_sub_u32 s87, s87, 1
	s_nop 3
	v_readlane_b32 s83, v42, s87
	v_readlane_b32 s76, v43, s87
	v_readlane_b32 s77, v44, s87
	v_readlane_b32 s78, v45, s87
	v_readlane_b32 s79, v46, s87
	v_readlane_b32 s80, v47, s87
	v_readlane_b32 s81, v48, s87
	v_readlane_b32 s82, v49, s87
	s_nop 3
	s_sub_u32 s92, s84, s83
	s_lshr_b32 s93, s80, 6
	s_mov_b32 s94, 0x10000000
	s_cmp_eq_u32 s93, 6
	s_cselect_b32 s94, 0x2aaaaaab, s94
	s_cmp_eq_u32 s93, 4
	s_cselect_b32 s94, 0x40000000, s94
	s_cmp_eq_u32 s93, 44
	s_cselect_b32 s94, 0x5d1745e, s94
	s_cmp_eq_u32 s93, 32
	s_cselect_b32 s94, 0x8000000, s94
	s_mul_hi_u32 s95, s92, s94
	s_mul_i32 s96, s95, s93
	s_sub_u32 s96, s92, s96
	s_lshl_b32 s95, s95, 6
	s_lshl_b32 s96, s96, 6
	s_cmp_lt_u32 s95, s81
	s_cselect_b32 s97, -1, 0
	s_cselect_b32 s74, s95, 0
	v_add_u32_e32 v104, s95, v53
	v_mul_lo_u32 v104, v104, s80
	v_add3_u32 v104, v104, v54, s96
	v_lshlrev_b32_e32 v104, 1, v104
	v_mov_b32_e32 v105, 0
	v_lshl_add_u64 v[88:89], v[104:105], 0, s[78:79]
	v_mov_b32_e32 v90, s97
	v_add_u32_e32 v104, s74, v50
	s_cmp_eq_u32 s82, 0
	s_cbranch_scc1 .Lcvs_sc_done_p2
	s_cmp_eq_u32 s82, 2
	s_cbranch_scc1 .Lcvs_sc_m2_p2
	s_cmpk_lt_u32 s74, 0x400
	s_cbranch_scc1 .Lcvs_sc_done_p2
	v_add_u32_e32 v104, 0xfffffc00, v104
	v_lshrrev_b32_e32 v105, 5, v104
	v_lshlrev_b32_e32 v105, 4, v105
	v_and_b32_e32 v106, 15, v104
	v_bfe_u32 v107, v104, 4, 1
	v_lshlrev_b32_e32 v107, 10, v107
	v_add3_u32 v104, v105, v106, v107
	v_add_u32_e32 v104, 0x400, v104
	s_branch .Lcvs_sc_done_p2

.Lcvs_sc_done_p2:
	v_add_u32_e32 v105, s96, v51
	v_mul_lo_u32 v105, v105, s81
	v_add_lshl_u32 v80, v105, v104, 2
	s_lshl_b32 s75, s81, 2
	v_add_u32_e32 v81, s75, v80
	v_add_u32_e32 v82, s75, v81
	v_add_u32_e32 v83, s75, v82
	v_add_u32_e32 v84, s75, v83
	v_add_u32_e32 v85, s75, v84
	v_add_u32_e32 v86, s75, v85
	v_add_u32_e32 v87, s75, v86
	global_load_dword v80, v80, s[76:77]
	global_load_dword v81, v81, s[76:77]
	global_load_dword v82, v82, s[76:77]
	global_load_dword v83, v83, s[76:77]
	global_load_dword v84, v84, s[76:77]
	global_load_dword v85, v85, s[76:77]
	global_load_dword v86, v86, s[76:77]
	global_load_dword v87, v87, s[76:77]
	s_add_i32 s84, s84, s70
	s_cmp_ge_i32 s84, s71
	s_cbranch_scc1 .Lcvs_pro_done
	v_cmp_le_i32_e64 s[88:89], v42, s84
	s_nop 1
	s_bcnt1_i32_b64 s87, s[88:89]
	s_sub_u32 s87, s87, 1
	s_nop 3
	v_readlane_b32 s83, v42, s87
	v_readlane_b32 s76, v43, s87
	v_readlane_b32 s77, v44, s87
	v_readlane_b32 s78, v45, s87
	v_readlane_b32 s79, v46, s87
	v_readlane_b32 s80, v47, s87
	v_readlane_b32 s81, v48, s87
	v_readlane_b32 s82, v49, s87
	s_nop 3
	s_sub_u32 s92, s84, s83
	s_lshr_b32 s93, s80, 6
	s_mov_b32 s94, 0x10000000
	s_cmp_eq_u32 s93, 6
	s_cselect_b32 s94, 0x2aaaaaab, s94
	s_cmp_eq_u32 s93, 4
	s_cselect_b32 s94, 0x40000000, s94
	s_cmp_eq_u32 s93, 44
	s_cselect_b32 s94, 0x5d1745e, s94
	s_cmp_eq_u32 s93, 32
	s_cselect_b32 s94, 0x8000000, s94
	s_mul_hi_u32 s95, s92, s94
	s_mul_i32 s96, s95, s93
	s_sub_u32 s96, s92, s96
	s_lshl_b32 s95, s95, 6
	s_lshl_b32 s96, s96, 6
	s_cmp_lt_u32 s95, s81
	s_cselect_b32 s97, -1, 0
	s_cselect_b32 s74, s95, 0
	v_add_u32_e32 v104, s95, v53
	v_mul_lo_u32 v104, v104, s80
	v_add3_u32 v104, v104, v54, s96
	v_lshlrev_b32_e32 v104, 1, v104
	v_mov_b32_e32 v105, 0
	v_lshl_add_u64 v[100:101], v[104:105], 0, s[78:79]
	v_mov_b32_e32 v102, s97
	v_add_u32_e32 v104, s74, v50
	s_cmp_eq_u32 s82, 0
	s_cbranch_scc1 .Lcvs_sc_done_p3
	s_cmp_eq_u32 s82, 2
	s_cbranch_scc1 .Lcvs_sc_m2_p3
	s_cmpk_lt_u32 s74, 0x400
	s_cbranch_scc1 .Lcvs_sc_done_p3
	v_add_u32_e32 v104, 0xfffffc00, v104
	v_lshrrev_b32_e32 v105, 5, v104
	v_lshlrev_b32_e32 v105, 4, v105
	v_and_b32_e32 v106, 15, v104
	v_bfe_u32 v107, v104, 4, 1
	v_lshlrev_b32_e32 v107, 10, v107
	v_add3_u32 v104, v105, v106, v107
	v_add_u32_e32 v104, 0x400, v104
	s_branch .Lcvs_sc_done_p3

.Lcvs_sc_done_p3:
	v_add_u32_e32 v105, s96, v51
	v_mul_lo_u32 v105, v105, s81
	v_add_lshl_u32 v92, v105, v104, 2
	s_lshl_b32 s75, s81, 2
	v_add_u32_e32 v93, s75, v92
	v_add_u32_e32 v94, s75, v93
	v_add_u32_e32 v95, s75, v94
	v_add_u32_e32 v96, s75, v95
	v_add_u32_e32 v97, s75, v96
	v_add_u32_e32 v98, s75, v97
	v_add_u32_e32 v99, s75, v98
	global_load_dword v92, v92, s[76:77]
	global_load_dword v93, v93, s[76:77]
	global_load_dword v94, v94, s[76:77]
	global_load_dword v95, v95, s[76:77]
	global_load_dword v96, v96, s[76:77]
	global_load_dword v97, v97, s[76:77]
	global_load_dword v98, v98, s[76:77]
	global_load_dword v99, v99, s[76:77]
	s_add_i32 s84, s84, s70
.Lcvs_pro_done:
.Lcvs_loop:
	s_cmp_ge_i32 s85, s71
	s_cbranch_scc1 .Lcvs_done
	s_add_i32 s87, s85, s86
	s_cmp_lt_i32 s87, s71
	s_cbranch_scc1 .Lcvs_w24_0
	s_waitcnt vmcnt(0)
	s_branch .Lcvs_go_0

.Lcvs_go_0:
	v_and_b32_e32 v56, v66, v56
	v_and_b32_e32 v57, v66, v57
	v_and_b32_e32 v58, v66, v58
	v_and_b32_e32 v59, v66, v59
	v_and_b32_e32 v60, v66, v60
	v_and_b32_e32 v61, v66, v61
	v_and_b32_e32 v62, v66, v62
	v_and_b32_e32 v63, v66, v63
	ds_write_b32 v52, v56 offset:0
	ds_write_b32 v52, v57 offset:260
	ds_write_b32 v52, v58 offset:520
	ds_write_b32 v52, v59 offset:780
	ds_write_b32 v52, v60 offset:1040
	ds_write_b32 v52, v61 offset:1300
	ds_write_b32 v52, v62 offset:1560
	ds_write_b32 v52, v63 offset:1820
	s_waitcnt lgkmcnt(0)
	s_barrier
	ds_read2_b32 v[112:113], v55 offset1:65
	ds_read2_b32 v[114:115], v55 offset0:130 offset1:195
	ds_read2_b32 v[116:117], v67 offset1:65
	ds_read2_b32 v[118:119], v67 offset0:130 offset1:195
	s_waitcnt lgkmcnt(3)
	v_cvt_pk_bf16_f32 v108, v112, v113
	s_waitcnt lgkmcnt(2)
	v_cvt_pk_bf16_f32 v109, v114, v115
	s_waitcnt lgkmcnt(1)
	v_cvt_pk_bf16_f32 v110, v116, v117
	s_waitcnt lgkmcnt(0)
	v_cvt_pk_bf16_f32 v111, v118, v119
	global_store_dwordx4 v[64:65], v[108:111], off
	s_add_i32 s85, s85, s70
	s_cmp_ge_i32 s84, s71
	s_cbranch_scc1 .Lcvs_nodec_0
	v_cmp_le_i32_e64 s[88:89], v42, s84
	s_nop 1
	s_bcnt1_i32_b64 s87, s[88:89]
	s_sub_u32 s87, s87, 1
	s_nop 3
	v_readlane_b32 s83, v42, s87
	v_readlane_b32 s76, v43, s87
	v_readlane_b32 s77, v44, s87
	v_readlane_b32 s78, v45, s87
	v_readlane_b32 s79, v46, s87
	v_readlane_b32 s80, v47, s87
	v_readlane_b32 s81, v48, s87
	v_readlane_b32 s82, v49, s87
	s_nop 3
	s_sub_u32 s92, s84, s83
	s_lshr_b32 s93, s80, 6
	s_mov_b32 s94, 0x10000000
	s_cmp_eq_u32 s93, 6
	s_cselect_b32 s94, 0x2aaaaaab, s94
	s_cmp_eq_u32 s93, 4
	s_cselect_b32 s94, 0x40000000, s94
	s_cmp_eq_u32 s93, 44
	s_cselect_b32 s94, 0x5d1745e, s94
	s_cmp_eq_u32 s93, 32
	s_cselect_b32 s94, 0x8000000, s94
	s_mul_hi_u32 s95, s92, s94
	s_mul_i32 s96, s95, s93
	s_sub_u32 s96, s92, s96
	s_lshl_b32 s95, s95, 6
	s_lshl_b32 s96, s96, 6
	s_cmp_lt_u32 s95, s81
	s_cselect_b32 s97, -1, 0
	s_cselect_b32 s74, s95, 0
	v_add_u32_e32 v104, s95, v53
	v_mul_lo_u32 v104, v104, s80
	v_add3_u32 v104, v104, v54, s96
	v_lshlrev_b32_e32 v104, 1, v104
	v_mov_b32_e32 v105, 0
	v_lshl_add_u64 v[64:65], v[104:105], 0, s[78:79]
	v_mov_b32_e32 v66, s97
	v_add_u32_e32 v104, s74, v50
	s_cmp_eq_u32 s82, 0
	s_cbranch_scc1 .Lcvs_sc_done_l0
	s_cmp_eq_u32 s82, 2
	s_cbranch_scc1 .Lcvs_sc_m2_l0
	s_cmpk_lt_u32 s74, 0x400
	s_cbranch_scc1 .Lcvs_sc_done_l0
	v_add_u32_e32 v104, 0xfffffc00, v104
	v_lshrrev_b32_e32 v105, 5, v104
	v_lshlrev_b32_e32 v105, 4, v105
	v_and_b32_e32 v106, 15, v104
	v_bfe_u32 v107, v104, 4, 1
	v_lshlrev_b32_e32 v107, 10, v107
	v_add3_u32 v104, v105, v106, v107
	v_add_u32_e32 v104, 0x400, v104
	s_branch .Lcvs_sc_done_l0

.Lcvs_sc_done_l0:
	v_add_u32_e32 v105, s96, v51
	v_mul_lo_u32 v105, v105, s81
	v_add_lshl_u32 v56, v105, v104, 2
	s_lshl_b32 s75, s81, 2
	v_add_u32_e32 v57, s75, v56
	v_add_u32_e32 v58, s75, v57
	v_add_u32_e32 v59, s75, v58
	v_add_u32_e32 v60, s75, v59
	v_add_u32_e32 v61, s75, v60
	v_add_u32_e32 v62, s75, v61
	v_add_u32_e32 v63, s75, v62
	global_load_dword v56, v56, s[76:77]
	global_load_dword v57, v57, s[76:77]
	global_load_dword v58, v58, s[76:77]
	global_load_dword v59, v59, s[76:77]
	global_load_dword v60, v60, s[76:77]
	global_load_dword v61, v61, s[76:77]
	global_load_dword v62, v62, s[76:77]
	global_load_dword v63, v63, s[76:77]
	s_add_i32 s84, s84, s70
.Lcvs_nodec_0:
	s_cmp_ge_i32 s85, s71
	s_cbranch_scc1 .Lcvs_done
	s_add_i32 s87, s85, s86
	s_cmp_lt_i32 s87, s71
	s_cbranch_scc1 .Lcvs_w24_1
	s_waitcnt vmcnt(0)
	s_branch .Lcvs_go_1

.Lcvs_go_1:
	v_and_b32_e32 v68, v78, v68
	v_and_b32_e32 v69, v78, v69
	v_and_b32_e32 v70, v78, v70
	v_and_b32_e32 v71, v78, v71
	v_and_b32_e32 v72, v78, v72
	v_and_b32_e32 v73, v78, v73
	v_and_b32_e32 v74, v78, v74
	v_and_b32_e32 v75, v78, v75
	ds_write_b32 v52, v68 offset:16640
	ds_write_b32 v52, v69 offset:16900
	ds_write_b32 v52, v70 offset:17160
	ds_write_b32 v52, v71 offset:17420
	ds_write_b32 v52, v72 offset:17680
	ds_write_b32 v52, v73 offset:17940
	ds_write_b32 v52, v74 offset:18200
	ds_write_b32 v52, v75 offset:18460
	s_waitcnt lgkmcnt(0)
	s_barrier
	ds_read2_b32 v[112:113], v79 offset1:65
	ds_read2_b32 v[114:115], v79 offset0:130 offset1:195
	ds_read2_b32 v[116:117], v91 offset1:65
	ds_read2_b32 v[118:119], v91 offset0:130 offset1:195
	s_waitcnt lgkmcnt(3)
	v_cvt_pk_bf16_f32 v108, v112, v113
	s_waitcnt lgkmcnt(2)
	v_cvt_pk_bf16_f32 v109, v114, v115
	s_waitcnt lgkmcnt(1)
	v_cvt_pk_bf16_f32 v110, v116, v117
	s_waitcnt lgkmcnt(0)
	v_cvt_pk_bf16_f32 v111, v118, v119
	global_store_dwordx4 v[76:77], v[108:111], off
	s_add_i32 s85, s85, s70
	s_cmp_ge_i32 s84, s71
	s_cbranch_scc1 .Lcvs_nodec_1
	v_cmp_le_i32_e64 s[88:89], v42, s84
	s_nop 1
	s_bcnt1_i32_b64 s87, s[88:89]
	s_sub_u32 s87, s87, 1
	s_nop 3
	v_readlane_b32 s83, v42, s87
	v_readlane_b32 s76, v43, s87
	v_readlane_b32 s77, v44, s87
	v_readlane_b32 s78, v45, s87
	v_readlane_b32 s79, v46, s87
	v_readlane_b32 s80, v47, s87
	v_readlane_b32 s81, v48, s87
	v_readlane_b32 s82, v49, s87
	s_nop 3
	s_sub_u32 s92, s84, s83
	s_lshr_b32 s93, s80, 6
	s_mov_b32 s94, 0x10000000
	s_cmp_eq_u32 s93, 6
	s_cselect_b32 s94, 0x2aaaaaab, s94
	s_cmp_eq_u32 s93, 4
	s_cselect_b32 s94, 0x40000000, s94
	s_cmp_eq_u32 s93, 44
	s_cselect_b32 s94, 0x5d1745e, s94
	s_cmp_eq_u32 s93, 32
	s_cselect_b32 s94, 0x8000000, s94
	s_mul_hi_u32 s95, s92, s94
	s_mul_i32 s96, s95, s93
	s_sub_u32 s96, s92, s96
	s_lshl_b32 s95, s95, 6
	s_lshl_b32 s96, s96, 6
	s_cmp_lt_u32 s95, s81
	s_cselect_b32 s97, -1, 0
	s_cselect_b32 s74, s95, 0
	v_add_u32_e32 v104, s95, v53
	v_mul_lo_u32 v104, v104, s80
	v_add3_u32 v104, v104, v54, s96
	v_lshlrev_b32_e32 v104, 1, v104
	v_mov_b32_e32 v105, 0
	v_lshl_add_u64 v[76:77], v[104:105], 0, s[78:79]
	v_mov_b32_e32 v78, s97
	v_add_u32_e32 v104, s74, v50
	s_cmp_eq_u32 s82, 0
	s_cbranch_scc1 .Lcvs_sc_done_l1
	s_cmp_eq_u32 s82, 2
	s_cbranch_scc1 .Lcvs_sc_m2_l1
	s_cmpk_lt_u32 s74, 0x400
	s_cbranch_scc1 .Lcvs_sc_done_l1
	v_add_u32_e32 v104, 0xfffffc00, v104
	v_lshrrev_b32_e32 v105, 5, v104
	v_lshlrev_b32_e32 v105, 4, v105
	v_and_b32_e32 v106, 15, v104
	v_bfe_u32 v107, v104, 4, 1
	v_lshlrev_b32_e32 v107, 10, v107
	v_add3_u32 v104, v105, v106, v107
	v_add_u32_e32 v104, 0x400, v104
	s_branch .Lcvs_sc_done_l1

.Lcvs_sc_done_l1:
	v_add_u32_e32 v105, s96, v51
	v_mul_lo_u32 v105, v105, s81
	v_add_lshl_u32 v68, v105, v104, 2
	s_lshl_b32 s75, s81, 2
	v_add_u32_e32 v69, s75, v68
	v_add_u32_e32 v70, s75, v69
	v_add_u32_e32 v71, s75, v70
	v_add_u32_e32 v72, s75, v71
	v_add_u32_e32 v73, s75, v72
	v_add_u32_e32 v74, s75, v73
	v_add_u32_e32 v75, s75, v74
	global_load_dword v68, v68, s[76:77]
	global_load_dword v69, v69, s[76:77]
	global_load_dword v70, v70, s[76:77]
	global_load_dword v71, v71, s[76:77]
	global_load_dword v72, v72, s[76:77]
	global_load_dword v73, v73, s[76:77]
	global_load_dword v74, v74, s[76:77]
	global_load_dword v75, v75, s[76:77]
	s_add_i32 s84, s84, s70

.Lcvs_go_2:
	v_and_b32_e32 v80, v90, v80
	v_and_b32_e32 v81, v90, v81
	v_and_b32_e32 v82, v90, v82
	v_and_b32_e32 v83, v90, v83
	v_and_b32_e32 v84, v90, v84
	v_and_b32_e32 v85, v90, v85
	v_and_b32_e32 v86, v90, v86
	v_and_b32_e32 v87, v90, v87
	ds_write_b32 v52, v80 offset:0
	ds_write_b32 v52, v81 offset:260
	ds_write_b32 v52, v82 offset:520
	ds_write_b32 v52, v83 offset:780
	ds_write_b32 v52, v84 offset:1040
	ds_write_b32 v52, v85 offset:1300
	ds_write_b32 v52, v86 offset:1560
	ds_write_b32 v52, v87 offset:1820
	s_waitcnt lgkmcnt(0)
	s_barrier
	ds_read2_b32 v[112:113], v55 offset1:65
	ds_read2_b32 v[114:115], v55 offset0:130 offset1:195
	ds_read2_b32 v[116:117], v67 offset1:65
	ds_read2_b32 v[118:119], v67 offset0:130 offset1:195
	s_waitcnt lgkmcnt(3)
	v_cvt_pk_bf16_f32 v108, v112, v113
	s_waitcnt lgkmcnt(2)
	v_cvt_pk_bf16_f32 v109, v114, v115
	s_waitcnt lgkmcnt(1)
	v_cvt_pk_bf16_f32 v110, v116, v117
	s_waitcnt lgkmcnt(0)
	v_cvt_pk_bf16_f32 v111, v118, v119
	global_store_dwordx4 v[88:89], v[108:111], off
	s_add_i32 s85, s85, s70
	s_cmp_ge_i32 s84, s71
	s_cbranch_scc1 .Lcvs_nodec_2
	v_cmp_le_i32_e64 s[88:89], v42, s84
	s_nop 1
	s_bcnt1_i32_b64 s87, s[88:89]
	s_sub_u32 s87, s87, 1
	s_nop 3
	v_readlane_b32 s83, v42, s87
	v_readlane_b32 s76, v43, s87
	v_readlane_b32 s77, v44, s87
	v_readlane_b32 s78, v45, s87
	v_readlane_b32 s79, v46, s87
	v_readlane_b32 s80, v47, s87
	v_readlane_b32 s81, v48, s87
	v_readlane_b32 s82, v49, s87
	s_nop 3
	s_sub_u32 s92, s84, s83
	s_lshr_b32 s93, s80, 6
	s_mov_b32 s94, 0x10000000
	s_cmp_eq_u32 s93, 6
	s_cselect_b32 s94, 0x2aaaaaab, s94
	s_cmp_eq_u32 s93, 4
	s_cselect_b32 s94, 0x40000000, s94
	s_cmp_eq_u32 s93, 44
	s_cselect_b32 s94, 0x5d1745e, s94
	s_cmp_eq_u32 s93, 32
	s_cselect_b32 s94, 0x8000000, s94
	s_mul_hi_u32 s95, s92, s94
	s_mul_i32 s96, s95, s93
	s_sub_u32 s96, s92, s96
	s_lshl_b32 s95, s95, 6
	s_lshl_b32 s96, s96, 6
	s_cmp_lt_u32 s95, s81
	s_cselect_b32 s97, -1, 0
	s_cselect_b32 s74, s95, 0
	v_add_u32_e32 v104, s95, v53
	v_mul_lo_u32 v104, v104, s80
	v_add3_u32 v104, v104, v54, s96
	v_lshlrev_b32_e32 v104, 1, v104
	v_mov_b32_e32 v105, 0
	v_lshl_add_u64 v[88:89], v[104:105], 0, s[78:79]
	v_mov_b32_e32 v90, s97
	v_add_u32_e32 v104, s74, v50
	s_cmp_eq_u32 s82, 0
	s_cbranch_scc1 .Lcvs_sc_done_l2
	s_cmp_eq_u32 s82, 2
	s_cbranch_scc1 .Lcvs_sc_m2_l2
	s_cmpk_lt_u32 s74, 0x400
	s_cbranch_scc1 .Lcvs_sc_done_l2
	v_add_u32_e32 v104, 0xfffffc00, v104
	v_lshrrev_b32_e32 v105, 5, v104
	v_lshlrev_b32_e32 v105, 4, v105
	v_and_b32_e32 v106, 15, v104
	v_bfe_u32 v107, v104, 4, 1
	v_lshlrev_b32_e32 v107, 10, v107
	v_add3_u32 v104, v105, v106, v107
	v_add_u32_e32 v104, 0x400, v104
	s_branch .Lcvs_sc_done_l2

.Lcvs_sc_done_l2:
	v_add_u32_e32 v105, s96, v51
	v_mul_lo_u32 v105, v105, s81
	v_add_lshl_u32 v80, v105, v104, 2
	s_lshl_b32 s75, s81, 2
	v_add_u32_e32 v81, s75, v80
	v_add_u32_e32 v82, s75, v81
	v_add_u32_e32 v83, s75, v82
	v_add_u32_e32 v84, s75, v83
	v_add_u32_e32 v85, s75, v84
	v_add_u32_e32 v86, s75, v85
	v_add_u32_e32 v87, s75, v86
	global_load_dword v80, v80, s[76:77]
	global_load_dword v81, v81, s[76:77]
	global_load_dword v82, v82, s[76:77]
	global_load_dword v83, v83, s[76:77]
	global_load_dword v84, v84, s[76:77]
	global_load_dword v85, v85, s[76:77]
	global_load_dword v86, v86, s[76:77]
	global_load_dword v87, v87, s[76:77]
	s_add_i32 s84, s84, s70

.Lcvs_go_3:
	v_and_b32_e32 v92, v102, v92
	v_and_b32_e32 v93, v102, v93
	v_and_b32_e32 v94, v102, v94
	v_and_b32_e32 v95, v102, v95
	v_and_b32_e32 v96, v102, v96
	v_and_b32_e32 v97, v102, v97
	v_and_b32_e32 v98, v102, v98
	v_and_b32_e32 v99, v102, v99
	ds_write_b32 v52, v92 offset:16640
	ds_write_b32 v52, v93 offset:16900
	ds_write_b32 v52, v94 offset:17160
	ds_write_b32 v52, v95 offset:17420
	ds_write_b32 v52, v96 offset:17680
	ds_write_b32 v52, v97 offset:17940
	ds_write_b32 v52, v98 offset:18200
	ds_write_b32 v52, v99 offset:18460
	s_waitcnt lgkmcnt(0)
	s_barrier
	ds_read2_b32 v[112:113], v79 offset1:65
	ds_read2_b32 v[114:115], v79 offset0:130 offset1:195
	ds_read2_b32 v[116:117], v91 offset1:65
	ds_read2_b32 v[118:119], v91 offset0:130 offset1:195
	s_waitcnt lgkmcnt(3)
	v_cvt_pk_bf16_f32 v108, v112, v113
	s_waitcnt lgkmcnt(2)
	v_cvt_pk_bf16_f32 v109, v114, v115
	s_waitcnt lgkmcnt(1)
	v_cvt_pk_bf16_f32 v110, v116, v117
	s_waitcnt lgkmcnt(0)
	v_cvt_pk_bf16_f32 v111, v118, v119
	global_store_dwordx4 v[100:101], v[108:111], off
	s_add_i32 s85, s85, s70
	s_cmp_ge_i32 s84, s71
	s_cbranch_scc1 .Lcvs_nodec_3
	v_cmp_le_i32_e64 s[88:89], v42, s84
	s_nop 1
	s_bcnt1_i32_b64 s87, s[88:89]
	s_sub_u32 s87, s87, 1
	s_nop 3
	v_readlane_b32 s83, v42, s87
	v_readlane_b32 s76, v43, s87
	v_readlane_b32 s77, v44, s87
	v_readlane_b32 s78, v45, s87
	v_readlane_b32 s79, v46, s87
	v_readlane_b32 s80, v47, s87
	v_readlane_b32 s81, v48, s87
	v_readlane_b32 s82, v49, s87
	s_nop 3
	s_sub_u32 s92, s84, s83
	s_lshr_b32 s93, s80, 6
	s_mov_b32 s94, 0x10000000
	s_cmp_eq_u32 s93, 6
	s_cselect_b32 s94, 0x2aaaaaab, s94
	s_cmp_eq_u32 s93, 4
	s_cselect_b32 s94, 0x40000000, s94
	s_cmp_eq_u32 s93, 44
	s_cselect_b32 s94, 0x5d1745e, s94
	s_cmp_eq_u32 s93, 32
	s_cselect_b32 s94, 0x8000000, s94
	s_mul_hi_u32 s95, s92, s94
	s_mul_i32 s96, s95, s93
	s_sub_u32 s96, s92, s96
	s_lshl_b32 s95, s95, 6
	s_lshl_b32 s96, s96, 6
	s_cmp_lt_u32 s95, s81
	s_cselect_b32 s97, -1, 0
	s_cselect_b32 s74, s95, 0
	v_add_u32_e32 v104, s95, v53
	v_mul_lo_u32 v104, v104, s80
	v_add3_u32 v104, v104, v54, s96
	v_lshlrev_b32_e32 v104, 1, v104
	v_mov_b32_e32 v105, 0
	v_lshl_add_u64 v[100:101], v[104:105], 0, s[78:79]
	v_mov_b32_e32 v102, s97
	v_add_u32_e32 v104, s74, v50
	s_cmp_eq_u32 s82, 0
	s_cbranch_scc1 .Lcvs_sc_done_l3
	s_cmp_eq_u32 s82, 2
	s_cbranch_scc1 .Lcvs_sc_m2_l3
	s_cmpk_lt_u32 s74, 0x400
	s_cbranch_scc1 .Lcvs_sc_done_l3
	v_add_u32_e32 v104, 0xfffffc00, v104
	v_lshrrev_b32_e32 v105, 5, v104
	v_lshlrev_b32_e32 v105, 4, v105
	v_and_b32_e32 v106, 15, v104
	v_bfe_u32 v107, v104, 4, 1
	v_lshlrev_b32_e32 v107, 10, v107
	v_add3_u32 v104, v105, v106, v107
	v_add_u32_e32 v104, 0x400, v104
	s_branch .Lcvs_sc_done_l3

.Lcvs_done:
	s_waitcnt vmcnt(0)
	s_barrier
	v_readlane_b32 s68, v250, 0
	v_readlane_b32 s69, v250, 1
	v_readlane_b32 s70, v250, 2
	v_readlane_b32 s71, v250, 3
	v_readlane_b32 s72, v250, 4
	v_readlane_b32 s74, v250, 5
	v_readlane_b32 s75, v250, 6
	v_readlane_b32 s76, v250, 7
	v_readlane_b32 s77, v250, 8
	v_readlane_b32 s78, v250, 9
	v_readlane_b32 s79, v250, 10
	v_readlane_b32 s80, v250, 11
	v_readlane_b32 s81, v250, 12
	v_readlane_b32 s82, v250, 13
	v_readlane_b32 s83, v250, 14
	v_readlane_b32 s84, v250, 15
	v_readlane_b32 s85, v250, 16
	v_readlane_b32 s86, v250, 17
	v_readlane_b32 s87, v250, 18
	v_readlane_b32 s88, v250, 19
	v_readlane_b32 s89, v250, 20
	v_readlane_b32 s90, v250, 21
	v_readlane_b32 s91, v250, 22
	v_readlane_b32 s92, v250, 23
	v_readlane_b32 s93, v250, 24
	v_readlane_b32 s94, v250, 25
	v_readlane_b32 s95, v250, 26
	v_readlane_b32 s96, v250, 27
	v_readlane_b32 s97, v250, 28
	s_nop 3
	s_branch .LBB0_319
	v_bfe_i32 v0, v11, 4, 1
	v_and_b32_e32 v2, 15, v11
	s_movk_i32 s6, 0xb00
	v_and_or_b32 v20, v0, s6, v2
	v_lshlrev_b32_e32 v0, 6, v11
	s_movk_i32 s6, 0x400
	v_and_b32_e32 v19, 63, v11
	v_and_or_b32 v0, v0, s6, v2
	v_ashrrev_i32_e32 v22, 3, v11
	v_add_u32_e32 v21, 0x400, v0
	v_and_b32_e32 v23, -8, v22
	v_lshlrev_b32_e32 v0, 2, v19
	s_movk_i32 s8, 0x104
	v_or_b32_e32 v35, 7, v22
	v_mad_u64_u32 v[6:7], s[6:7], v23, s8, v[0:1]
	v_mad_u64_u32 v[8:9], s[6:7], v35, s8, v[0:1]
	v_lshlrev_b32_e32 v0, 3, v11
	v_and_b32_e32 v0, 56, v0
	v_mul_u32_u24_e32 v2, 0x41, v0
	v_lshlrev_b32_e32 v2, 2, v2
	v_or_b32_e32 v7, 1, v23
	v_add_u32_e32 v24, 0x104, v6
	v_or_b32_e32 v25, 2, v23
	v_add_u32_e32 v26, 0x208, v6
	v_or_b32_e32 v27, 3, v23
	v_add_u32_e32 v28, 0x30c, v6
	v_or_b32_e32 v29, 4, v23
	v_add_u32_e32 v30, 0x410, v6
	v_or_b32_e32 v31, 5, v23
	v_add_u32_e32 v32, 0x514, v6
	v_or_b32_e32 v33, 6, v23
	v_add_u32_e32 v34, 0x618, v6
	v_lshl_add_u32 v9, v22, 2, v2
	s_mov_b64 s[62:63], 0
	v_lshlrev_b32_e32 v0, 1, v0
	v_mov_b32_e32 v10, v205
	s_branch .LBB0_299

.LBB0_327:
	v_mov_b32_e32 v130, s67
	v_mov_b32_e32 v131, s66
	v_cndmask_b32_e32 v130, v130, v131, vcc
	v_lshl_add_u32 v168, v130, 7, v155
	v_mov_b32_e32 v153, v161
	v_mov_b32_e32 v192, v181
	v_mov_b32_e32 v190, v183
	v_mov_b32_e32 v191, v182
	v_mov_b32_e32 v166, v157
	v_mov_b32_e32 v130, v186
	v_mov_b32_e32 v131, v187
	v_ashrrev_i32_e32 v169, 31, v168
	v_readfirstlane_b32 s64, v130
	v_readfirstlane_b32 s65, v131
	v_lshlrev_b64 v[130:131], 11, v[168:169]
	v_mov_b32_e32 v167, v189
	s_barrier
	v_lshl_add_u64 v[130:131], s[64:65], 0, v[130:131]
	v_lshl_add_u64 v[130:131], v[130:131], 0, v[0:1]
	v_lshlrev_b32_e32 v132, 4, v167
	v_and_b32_e32 v198, 0x1f0, v132
	v_mov_b32_e32 v199, v1
	v_lshlrev_b32_e32 v132, 6, v167
	v_lshl_add_u64 v[130:131], v[130:131], 0, v[198:199]
	v_and_b32_e32 v132, 0x3800, v132
	v_mov_b32_e32 v133, v1
	v_lshl_add_u64 v[208:209], v[130:131], 0, v[132:133]
	s_mov_b32 s6, 0xc640000
	v_add_co_u32_e64 v130, s[6:7], s6, v208
	v_bfe_u32 v167, v167, 5, 3
	s_nop 0
	v_addc_co_u32_e64 v131, s[6:7], 0, v209, s[6:7]
	s_mov_b32 s6, 0xc644000
	s_nop 0
	v_add_co_u32_e64 v134, s[6:7], s6, v208
	v_mul_u32_u24_e32 v167, 0x208, v167
	s_nop 0
	v_addc_co_u32_e64 v135, s[6:7], 0, v209, s[6:7]
	s_mov_b32 s6, 0xc648000
	s_nop 0
	v_add_co_u32_e64 v138, s[6:7], s6, v208
	global_load_dwordx4 v[130:133], v[130:131], off
	s_nop 0
	global_load_dwordx4 v[134:137], v[134:135], off
	v_addc_co_u32_e64 v139, s[6:7], 0, v209, s[6:7]
	s_mov_b32 s6, 0xc64c000
	s_nop 0
	v_add_co_u32_e64 v142, s[6:7], s6, v208
	v_add3_u32 v167, v149, v198, v167
	s_nop 0
	v_addc_co_u32_e64 v143, s[6:7], 0, v209, s[6:7]
	s_mov_b32 s6, 0xc650000
	s_nop 0
	v_add_co_u32_e64 v170, s[6:7], s6, v208
	global_load_dwordx4 v[138:141], v[138:139], off
	s_nop 0
	global_load_dwordx4 v[142:145], v[142:143], off
	v_addc_co_u32_e64 v171, s[6:7], 0, v209, s[6:7]
	s_mov_b32 s6, 0xc654000
	s_nop 0
	v_add_co_u32_e64 v194, s[6:7], s6, v208
	v_add_u32_e32 v193, 0x1040, v167
	s_nop 0
	v_addc_co_u32_e64 v195, s[6:7], 0, v209, s[6:7]
	s_mov_b32 s6, 0xc658000
	s_nop 0
	v_add_co_u32_e64 v210, s[6:7], s6, v208
	global_load_dwordx4 v[170:173], v[170:171], off
	s_nop 0
	global_load_dwordx4 v[194:197], v[194:195], off
	v_addc_co_u32_e64 v211, s[6:7], 0, v209, s[6:7]
	s_mov_b32 s6, 0xc65c000
	global_load_dwordx4 v[218:221], v[210:211], off
	v_add_co_u32_e64 v210, s[6:7], s6, v208
	v_add_u32_e32 v198, 0x2080, v167
	s_nop 0
	v_addc_co_u32_e64 v211, s[6:7], 0, v209, s[6:7]
	global_load_dwordx4 v[222:225], v[210:211], off
	v_add_u32_e32 v199, 0x30c0, v167
	v_add_u32_e32 v201, 0x4100, v167
	v_add_u32_e32 v217, 0x5140, v167
	v_lshl_add_u64 v[210:211], s[64:65], 0, v[162:163]
	s_waitcnt vmcnt(7)
	ds_write2_b64 v167, v[130:131], v[132:133] offset1:1
	s_waitcnt vmcnt(6)
	ds_write2_b64 v193, v[134:135], v[136:137] offset1:1
	s_waitcnt vmcnt(5)
	ds_write2_b64 v198, v[138:139], v[140:141] offset1:1
	s_waitcnt vmcnt(4)
	ds_write2_b64 v199, v[142:143], v[144:145] offset1:1
	s_waitcnt vmcnt(3)
	ds_write2_b64 v201, v[170:171], v[172:173] offset1:1
	s_waitcnt vmcnt(2)
	ds_write2_b64 v217, v[194:195], v[196:197] offset1:1
	v_add_u32_e32 v130, 0x6180, v167
	s_waitcnt vmcnt(1)
	ds_write2_b64 v130, v[218:219], v[220:221] offset1:1
	v_add_u32_e32 v130, 0x71c0, v167
	s_waitcnt vmcnt(0)
	ds_write2_b64 v130, v[222:223], v[224:225] offset1:1
	s_mov_b32 s6, 0xc660000
	v_add_co_u32_e64 v130, s[6:7], s6, v208
	v_add_u32_e32 v193, 0x8200, v167
	s_nop 0
	v_addc_co_u32_e64 v131, s[6:7], 0, v209, s[6:7]
	s_mov_b32 s6, 0xc664000
	s_nop 0
	v_add_co_u32_e64 v134, s[6:7], s6, v208
	global_load_dwordx4 v[130:133], v[130:131], off
	s_nop 0
	v_addc_co_u32_e64 v135, s[6:7], 0, v209, s[6:7]
	s_mov_b32 s6, 0xc668000
	s_nop 0
	v_add_co_u32_e64 v138, s[6:7], s6, v208
	global_load_dwordx4 v[134:137], v[134:135], off
	s_nop 0
	v_addc_co_u32_e64 v139, s[6:7], 0, v209, s[6:7]
	s_mov_b32 s6, 0xc66c000
	s_nop 0
	v_add_co_u32_e64 v142, s[6:7], s6, v208
	global_load_dwordx4 v[138:141], v[138:139], off
	s_nop 0
	v_addc_co_u32_e64 v143, s[6:7], 0, v209, s[6:7]
	s_mov_b32 s6, 0xc670000
	s_nop 0
	v_add_co_u32_e64 v170, s[6:7], s6, v208
	global_load_dwordx4 v[142:145], v[142:143], off
	s_nop 0
	v_addc_co_u32_e64 v171, s[6:7], 0, v209, s[6:7]
	s_mov_b32 s6, 0xc674000
	s_nop 0
	v_add_co_u32_e64 v194, s[6:7], s6, v208
	global_load_dwordx4 v[170:173], v[170:171], off
	s_nop 0
	v_addc_co_u32_e64 v195, s[6:7], 0, v209, s[6:7]
	s_mov_b32 s6, 0xc678000
	s_nop 0
	v_add_co_u32_e64 v198, s[6:7], s6, v208
	global_load_dwordx4 v[194:197], v[194:195], off
	s_nop 0
	v_addc_co_u32_e64 v199, s[6:7], 0, v209, s[6:7]
	s_mov_b32 s6, 0xc67c000
	global_load_dwordx4 v[218:221], v[198:199], off
	v_add_co_u32_e64 v198, s[6:7], s6, v208
	s_waitcnt vmcnt(6)
	ds_write2_b64 v193, v[130:131], v[132:133] offset1:1
	v_addc_co_u32_e64 v199, s[6:7], 0, v209, s[6:7]
	global_load_dwordx4 v[222:225], v[198:199], off
	v_add_u32_e32 v130, 0x9240, v167
	s_waitcnt vmcnt(6)
	ds_write2_b64 v130, v[134:135], v[136:137] offset1:1
	v_add_u32_e32 v130, 0xa280, v167
	s_waitcnt vmcnt(5)
	ds_write2_b64 v130, v[138:139], v[140:141] offset1:1
	v_add_u32_e32 v130, 0xb2c0, v167
	s_waitcnt vmcnt(4)
	ds_write2_b64 v130, v[142:143], v[144:145] offset1:1
	v_add_u32_e32 v130, 0xc300, v167
	s_waitcnt vmcnt(3)
	ds_write2_b64 v130, v[170:171], v[172:173] offset1:1
	v_add_u32_e32 v130, 0xd340, v167
	s_waitcnt vmcnt(2)
	ds_write2_b64 v130, v[194:195], v[196:197] offset1:1
	v_add_u32_e32 v130, 0xe380, v167
	s_waitcnt vmcnt(1)
	ds_write2_b64 v130, v[218:219], v[220:221] offset1:1
	v_add_u32_e32 v130, 0xf3c0, v167
	s_waitcnt vmcnt(0)
	ds_write2_b64 v130, v[222:223], v[224:225] offset1:1
	s_waitcnt lgkmcnt(0)
	s_barrier
	v_ashrrev_i32_e32 v167, 31, v166
	v_lshl_add_u64 v[130:131], v[166:167], 1, v[210:211]
	s_mov_b64 s[6:7], 0x8640000
	v_lshl_add_u64 v[170:171], v[130:131], 0, s[6:7]
	ds_read2_b64 v[130:133], v178 offset1:2
	ds_read2_b64 v[194:197], v178 offset0:4 offset1:6
	ds_read2_b64 v[218:221], v178 offset0:8 offset1:10
	v_or_b32_e32 v172, v168, v174
	v_ashrrev_i32_e32 v173, 31, v172
	ds_read2_b64 v[222:225], v178 offset0:12 offset1:14
	s_nop 0
	v_cvt_pk_bf16_f32 v134, v2, v3
	v_cvt_pk_bf16_f32 v135, v4, v5
	v_cvt_pk_bf16_f32 v136, v6, v7
	v_cvt_pk_bf16_f32 v137, v8, v9
	s_waitcnt lgkmcnt(3)
	s_nop 0
	v_mfma_f32_32x32x16_bf16 v[130:145], v[130:133], v[134:137], 0
	ds_read2_b64 v[226:229], v178 offset0:16 offset1:18
	s_nop 0
	v_cvt_pk_bf16_f32 v230, v10, v11
	v_cvt_pk_bf16_f32 v231, v12, v13
	v_cvt_pk_bf16_f32 v232, v14, v15
	v_cvt_pk_bf16_f32 v233, v16, v17
	s_waitcnt lgkmcnt(3)
	s_nop 0
	v_mfma_f32_32x32x16_bf16 v[130:145], v[194:197], v[230:233], v[130:145]
	ds_read2_b64 v[194:197], v178 offset0:20 offset1:22
	s_nop 0
	v_cvt_pk_bf16_f32 v230, v18, v19
	v_cvt_pk_bf16_f32 v231, v20, v21
	v_cvt_pk_bf16_f32 v232, v22, v23
	v_cvt_pk_bf16_f32 v233, v24, v25
	s_waitcnt lgkmcnt(3)
	s_nop 0
	v_mfma_f32_32x32x16_bf16 v[130:145], v[218:221], v[230:233], v[130:145]
	ds_read2_b64 v[218:221], v178 offset0:24 offset1:26
	s_nop 0
	v_cvt_pk_bf16_f32 v230, v26, v27
	v_cvt_pk_bf16_f32 v231, v28, v29
	v_cvt_pk_bf16_f32 v232, v30, v31
	v_cvt_pk_bf16_f32 v233, v32, v33
	s_waitcnt lgkmcnt(3)
	s_nop 0
	v_mfma_f32_32x32x16_bf16 v[130:145], v[222:225], v[230:233], v[130:145]
	ds_read2_b64 v[222:225], v178 offset0:28 offset1:30
	s_nop 0
	v_cvt_pk_bf16_f32 v230, v34, v35
	v_cvt_pk_bf16_f32 v231, v36, v37
	v_cvt_pk_bf16_f32 v232, v38, v39
	v_cvt_pk_bf16_f32 v233, v40, v41
	s_waitcnt lgkmcnt(3)
	s_nop 0
	v_mfma_f32_32x32x16_bf16 v[130:145], v[226:229], v[230:233], v[130:145]
	ds_read2_b64 v[226:229], v178 offset0:32 offset1:34
	s_nop 0
	v_cvt_pk_bf16_f32 v230, v42, v43
	v_cvt_pk_bf16_f32 v231, v44, v45
	v_cvt_pk_bf16_f32 v232, v46, v47
	v_cvt_pk_bf16_f32 v233, v48, v49
	s_waitcnt lgkmcnt(3)
	s_nop 0
	v_mfma_f32_32x32x16_bf16 v[130:145], v[194:197], v[230:233], v[130:145]
	ds_read2_b64 v[194:197], v178 offset0:36 offset1:38
	s_nop 0
	v_cvt_pk_bf16_f32 v230, v50, v51
	v_cvt_pk_bf16_f32 v231, v52, v53
	v_cvt_pk_bf16_f32 v232, v54, v55
	v_cvt_pk_bf16_f32 v233, v56, v57
	s_waitcnt lgkmcnt(3)
	s_nop 0
	v_mfma_f32_32x32x16_bf16 v[130:145], v[218:221], v[230:233], v[130:145]
	ds_read2_b64 v[218:221], v178 offset0:40 offset1:42
	s_nop 0
	v_cvt_pk_bf16_f32 v230, v58, v59
	v_cvt_pk_bf16_f32 v231, v60, v61
	v_cvt_pk_bf16_f32 v232, v62, v63
	v_cvt_pk_bf16_f32 v233, v64, v65
	s_waitcnt lgkmcnt(3)
	s_nop 0
	v_mfma_f32_32x32x16_bf16 v[130:145], v[222:225], v[230:233], v[130:145]
	ds_read2_b64 v[222:225], v178 offset0:44 offset1:46
	s_nop 0
	v_cvt_pk_bf16_f32 v230, v66, v67
	v_cvt_pk_bf16_f32 v231, v68, v69
	v_cvt_pk_bf16_f32 v232, v70, v71
	v_cvt_pk_bf16_f32 v233, v72, v73
	s_waitcnt lgkmcnt(3)
	s_nop 0
	v_mfma_f32_32x32x16_bf16 v[130:145], v[226:229], v[230:233], v[130:145]
	ds_read2_b64 v[226:229], v178 offset0:48 offset1:50
	s_nop 0
	v_cvt_pk_bf16_f32 v230, v74, v75
	v_cvt_pk_bf16_f32 v231, v76, v77
	v_cvt_pk_bf16_f32 v232, v78, v79
	v_cvt_pk_bf16_f32 v233, v80, v81
	s_waitcnt lgkmcnt(3)
	s_nop 0
	v_mfma_f32_32x32x16_bf16 v[130:145], v[194:197], v[230:233], v[130:145]
	ds_read2_b64 v[194:197], v178 offset0:52 offset1:54
	s_nop 0
	v_cvt_pk_bf16_f32 v230, v82, v83
	v_cvt_pk_bf16_f32 v231, v84, v85
	v_cvt_pk_bf16_f32 v232, v86, v87
	v_cvt_pk_bf16_f32 v233, v88, v89
	s_waitcnt lgkmcnt(3)
	s_nop 0
	v_mfma_f32_32x32x16_bf16 v[130:145], v[218:221], v[230:233], v[130:145]
	ds_read2_b64 v[218:221], v178 offset0:56 offset1:58
	s_nop 0
	v_cvt_pk_bf16_f32 v230, v90, v91
	v_cvt_pk_bf16_f32 v231, v92, v93
	v_cvt_pk_bf16_f32 v232, v94, v95
	v_cvt_pk_bf16_f32 v233, v96, v97
	s_waitcnt lgkmcnt(3)
	s_nop 0
	v_mfma_f32_32x32x16_bf16 v[130:145], v[222:225], v[230:233], v[130:145]
	ds_read2_b64 v[222:225], v178 offset0:60 offset1:62
	s_nop 0
	v_cvt_pk_bf16_f32 v230, v98, v99
	v_cvt_pk_bf16_f32 v231, v100, v101
	v_cvt_pk_bf16_f32 v232, v102, v103
	v_cvt_pk_bf16_f32 v233, v104, v105
	s_waitcnt lgkmcnt(3)
	s_nop 0
	v_mfma_f32_32x32x16_bf16 v[130:145], v[226:229], v[230:233], v[130:145]
	s_nop 0
	v_cvt_pk_bf16_f32 v226, v106, v107
	v_cvt_pk_bf16_f32 v227, v108, v109
	v_cvt_pk_bf16_f32 v228, v110, v111
	v_cvt_pk_bf16_f32 v229, v112, v113
	s_waitcnt lgkmcnt(2)
	s_nop 0
	v_mfma_f32_32x32x16_bf16 v[130:145], v[194:197], v[226:229], v[130:145]
	s_nop 0
	v_cvt_pk_bf16_f32 v194, v114, v115
	v_cvt_pk_bf16_f32 v195, v116, v117
	v_cvt_pk_bf16_f32 v196, v118, v119
	v_cvt_pk_bf16_f32 v197, v120, v121
	s_waitcnt lgkmcnt(1)
	s_nop 0
	v_mfma_f32_32x32x16_bf16 v[130:145], v[218:221], v[194:197], v[130:145]
	s_nop 0
	v_cvt_pk_bf16_f32 v194, v122, v123
	v_cvt_pk_bf16_f32 v195, v124, v125
	v_cvt_pk_bf16_f32 v196, v126, v127
	v_cvt_pk_bf16_f32 v197, v128, v129
	s_waitcnt lgkmcnt(0)
	s_nop 0
	v_mfma_f32_32x32x16_bf16 v[130:145], v[222:225], v[194:197], v[130:145]
	v_fma_f32 v193, 0, v192, v153
	v_exp_f32_e32 v193, v193
	v_lshlrev_b64 v[172:173], 12, v[172:173]
	v_lshl_add_u64 v[194:195], v[170:171], 0, v[172:173]
	s_nop 7
	v_mul_f32_e32 v130, v193, v130
	v_cvt_pk_bf16_f32 v130, v130, s0
	global_store_short v[194:195], v130, off
	v_add_f32_e32 v130, v153, v192
	v_exp_f32_e32 v130, v130
	s_nop 0
	v_mul_f32_e32 v130, v130, v131
	v_cvt_pk_bf16_f32 v193, v130, s0
	v_or_b32_e32 v130, 0x1000, v172
	v_mov_b32_e32 v131, v173
	v_lshl_add_u64 v[130:131], v[170:171], 0, v[130:131]
	global_store_short v[130:131], v193, off
	v_fma_f32 v130, 2.0, v192, v153
	v_exp_f32_e32 v130, v130
	v_mov_b32_e32 v131, v173
	v_mul_f32_e32 v130, v130, v132
	v_cvt_pk_bf16_f32 v132, v130, s0
	v_or_b32_e32 v130, 0x2000, v172
	v_lshl_add_u64 v[130:131], v[170:171], 0, v[130:131]
	global_store_short v[130:131], v132, off
	v_fmamk_f32 v130, v192, 0x40400000, v153
	v_exp_f32_e32 v130, v130
	v_mov_b32_e32 v131, v173
	v_mul_f32_e32 v130, v130, v133
	v_cvt_pk_bf16_f32 v132, v130, s0
	v_or_b32_e32 v130, 0x3000, v172
	v_lshl_add_u64 v[130:131], v[170:171], 0, v[130:131]
	global_store_short v[130:131], v132, off
	v_fmamk_f32 v130, v192, 0x41000000, v153
	v_exp_f32_e32 v130, v130
	v_mov_b32_e32 v131, v173
	v_mul_f32_e32 v130, v130, v134
	v_cvt_pk_bf16_f32 v132, v130, s0
	v_or_b32_e32 v130, 0x8000, v172
	v_lshl_add_u64 v[130:131], v[170:171], 0, v[130:131]
	global_store_short v[130:131], v132, off
	v_fmamk_f32 v130, v192, 0x41100000, v153
	v_exp_f32_e32 v130, v130
	v_mov_b32_e32 v131, v173
	v_mul_f32_e32 v130, v130, v135
	v_cvt_pk_bf16_f32 v132, v130, s0
	v_or_b32_e32 v130, 0x9000, v172
	v_lshl_add_u64 v[130:131], v[170:171], 0, v[130:131]
	global_store_short v[130:131], v132, off
	v_fmamk_f32 v130, v192, 0x41200000, v153
	v_exp_f32_e32 v130, v130
	v_mov_b32_e32 v131, v173
	v_mul_f32_e32 v130, v130, v136
	v_cvt_pk_bf16_f32 v132, v130, s0
	v_or_b32_e32 v130, 0xa000, v172
	v_lshl_add_u64 v[130:131], v[170:171], 0, v[130:131]
	global_store_short v[130:131], v132, off
	v_fmamk_f32 v130, v192, 0x41300000, v153
	v_exp_f32_e32 v130, v130
	v_mov_b32_e32 v131, v173
	v_mul_f32_e32 v130, v130, v137
	v_cvt_pk_bf16_f32 v132, v130, s0
	v_or_b32_e32 v130, 0xb000, v172
	v_lshl_add_u64 v[130:131], v[170:171], 0, v[130:131]
	global_store_short v[130:131], v132, off
	v_fmamk_f32 v130, v192, 0x41800000, v153
	v_exp_f32_e32 v130, v130
	v_mov_b32_e32 v131, v173
	v_mul_f32_e32 v130, v130, v138
	v_cvt_pk_bf16_f32 v132, v130, s0
	v_or_b32_e32 v130, 0x10000, v172
	v_lshl_add_u64 v[130:131], v[170:171], 0, v[130:131]
	global_store_short v[130:131], v132, off
	v_fmamk_f32 v130, v192, 0x41880000, v153
	v_exp_f32_e32 v130, v130
	v_mov_b32_e32 v131, v173
	v_mul_f32_e32 v130, v130, v139
	v_cvt_pk_bf16_f32 v132, v130, s0
	v_or_b32_e32 v130, 0x11000, v172
	v_lshl_add_u64 v[130:131], v[170:171], 0, v[130:131]
	global_store_short v[130:131], v132, off
	v_fmamk_f32 v130, v192, 0x41900000, v153
	v_exp_f32_e32 v130, v130
	v_mov_b32_e32 v131, v173
	v_mul_f32_e32 v130, v130, v140
	v_cvt_pk_bf16_f32 v132, v130, s0
	v_or_b32_e32 v130, 0x12000, v172
	v_lshl_add_u64 v[130:131], v[170:171], 0, v[130:131]
	global_store_short v[130:131], v132, off
	v_fmamk_f32 v130, v192, 0x41980000, v153
	v_exp_f32_e32 v130, v130
	v_mov_b32_e32 v131, v173
	v_mul_f32_e32 v130, v130, v141
	v_cvt_pk_bf16_f32 v132, v130, s0
	v_or_b32_e32 v130, 0x13000, v172
	v_lshl_add_u64 v[130:131], v[170:171], 0, v[130:131]
	global_store_short v[130:131], v132, off
	v_fmamk_f32 v130, v192, 0x41c00000, v153
	v_exp_f32_e32 v130, v130
	v_mov_b32_e32 v131, v173
	v_mul_f32_e32 v130, v130, v142
	v_cvt_pk_bf16_f32 v132, v130, s0
	v_or_b32_e32 v130, 0x18000, v172
	v_lshl_add_u64 v[130:131], v[170:171], 0, v[130:131]
	global_store_short v[130:131], v132, off
	v_fmamk_f32 v130, v192, 0x41c80000, v153
	v_exp_f32_e32 v130, v130
	v_mov_b32_e32 v131, v173
	v_mul_f32_e32 v130, v130, v143
	v_cvt_pk_bf16_f32 v132, v130, s0
	v_or_b32_e32 v130, 0x19000, v172
	v_lshl_add_u64 v[130:131], v[170:171], 0, v[130:131]
	global_store_short v[130:131], v132, off
	v_fmamk_f32 v130, v192, 0x41d00000, v153
	v_exp_f32_e32 v130, v130
	v_mov_b32_e32 v131, v173
	v_mul_f32_e32 v130, v130, v144
	v_cvt_pk_bf16_f32 v132, v130, s0
	v_or_b32_e32 v130, 0x1a000, v172
	v_lshl_add_u64 v[130:131], v[170:171], 0, v[130:131]
	global_store_short v[130:131], v132, off
	v_fmamk_f32 v130, v192, 0x41d80000, v153
	v_exp_f32_e32 v130, v130
	v_mov_b32_e32 v131, v173
	v_mul_f32_e32 v130, v130, v145
	v_cvt_pk_bf16_f32 v132, v130, s0
	v_or_b32_e32 v130, 0x1b000, v172
	v_lshl_add_u64 v[130:131], v[170:171], 0, v[130:131]
	global_store_short v[130:131], v132, off
	v_add_u32_e32 v193, 0x4000, v178
	ds_read2_b64 v[130:133], v193 offset0:32 offset1:34
	ds_read2_b64 v[194:197], v193 offset0:36 offset1:38
	ds_read2_b64 v[218:221], v193 offset0:40 offset1:42
	ds_read2_b64 v[222:225], v193 offset0:44 offset1:46
	s_nop 0
	v_cvt_pk_bf16_f32 v134, v2, v3
	v_cvt_pk_bf16_f32 v135, v4, v5
	v_cvt_pk_bf16_f32 v136, v6, v7
	v_cvt_pk_bf16_f32 v137, v8, v9
	s_waitcnt lgkmcnt(3)
	s_nop 0
	v_mfma_f32_32x32x16_bf16 v[130:145], v[130:133], v[134:137], 0
	ds_read2_b64 v[226:229], v193 offset0:48 offset1:50
	s_nop 0
	v_cvt_pk_bf16_f32 v230, v10, v11
	v_cvt_pk_bf16_f32 v231, v12, v13
	v_cvt_pk_bf16_f32 v232, v14, v15
	v_cvt_pk_bf16_f32 v233, v16, v17
	s_waitcnt lgkmcnt(3)
	s_nop 0
	v_mfma_f32_32x32x16_bf16 v[130:145], v[194:197], v[230:233], v[130:145]
	ds_read2_b64 v[194:197], v193 offset0:52 offset1:54
	s_nop 0
	v_cvt_pk_bf16_f32 v230, v18, v19
	v_cvt_pk_bf16_f32 v231, v20, v21
	v_cvt_pk_bf16_f32 v232, v22, v23
	v_cvt_pk_bf16_f32 v233, v24, v25
	s_waitcnt lgkmcnt(3)
	s_nop 0
	v_mfma_f32_32x32x16_bf16 v[130:145], v[218:221], v[230:233], v[130:145]
	ds_read2_b64 v[218:221], v193 offset0:56 offset1:58
	s_nop 0
	v_cvt_pk_bf16_f32 v230, v26, v27
	v_cvt_pk_bf16_f32 v231, v28, v29
	v_cvt_pk_bf16_f32 v232, v30, v31
	v_cvt_pk_bf16_f32 v233, v32, v33
	s_waitcnt lgkmcnt(3)
	s_nop 0
	v_mfma_f32_32x32x16_bf16 v[130:145], v[222:225], v[230:233], v[130:145]
	ds_read2_b64 v[222:225], v193 offset0:60 offset1:62
	s_nop 0
	v_cvt_pk_bf16_f32 v230, v34, v35
	v_cvt_pk_bf16_f32 v231, v36, v37
	v_cvt_pk_bf16_f32 v232, v38, v39
	v_cvt_pk_bf16_f32 v233, v40, v41
	s_waitcnt lgkmcnt(3)
	s_nop 0
	v_mfma_f32_32x32x16_bf16 v[130:145], v[226:229], v[230:233], v[130:145]
	ds_read2_b64 v[226:229], v193 offset0:64 offset1:66
	s_nop 0
	v_cvt_pk_bf16_f32 v230, v42, v43
	v_cvt_pk_bf16_f32 v231, v44, v45
	v_cvt_pk_bf16_f32 v232, v46, v47
	v_cvt_pk_bf16_f32 v233, v48, v49
	s_waitcnt lgkmcnt(3)
	s_nop 0
	v_mfma_f32_32x32x16_bf16 v[130:145], v[194:197], v[230:233], v[130:145]
	ds_read2_b64 v[194:197], v193 offset0:68 offset1:70
	s_nop 0
	v_cvt_pk_bf16_f32 v230, v50, v51
	v_cvt_pk_bf16_f32 v231, v52, v53
	v_cvt_pk_bf16_f32 v232, v54, v55
	v_cvt_pk_bf16_f32 v233, v56, v57
	s_waitcnt lgkmcnt(3)
	s_nop 0
	v_mfma_f32_32x32x16_bf16 v[130:145], v[218:221], v[230:233], v[130:145]
	ds_read2_b64 v[218:221], v193 offset0:72 offset1:74
	s_nop 0
	v_cvt_pk_bf16_f32 v230, v58, v59
	v_cvt_pk_bf16_f32 v231, v60, v61
	v_cvt_pk_bf16_f32 v232, v62, v63
	v_cvt_pk_bf16_f32 v233, v64, v65
	s_waitcnt lgkmcnt(3)
	s_nop 0
	v_mfma_f32_32x32x16_bf16 v[130:145], v[222:225], v[230:233], v[130:145]
	ds_read2_b64 v[222:225], v193 offset0:76 offset1:78
	s_nop 0
	v_cvt_pk_bf16_f32 v230, v66, v67
	v_cvt_pk_bf16_f32 v231, v68, v69
	v_cvt_pk_bf16_f32 v232, v70, v71
	v_cvt_pk_bf16_f32 v233, v72, v73
	s_waitcnt lgkmcnt(3)
	s_nop 0
	v_mfma_f32_32x32x16_bf16 v[130:145], v[226:229], v[230:233], v[130:145]
	ds_read2_b64 v[226:229], v193 offset0:80 offset1:82
	s_nop 0
	v_cvt_pk_bf16_f32 v230, v74, v75
	v_cvt_pk_bf16_f32 v231, v76, v77
	v_cvt_pk_bf16_f32 v232, v78, v79
	v_cvt_pk_bf16_f32 v233, v80, v81
	s_waitcnt lgkmcnt(3)
	s_nop 0
	v_mfma_f32_32x32x16_bf16 v[130:145], v[194:197], v[230:233], v[130:145]
	ds_read2_b64 v[194:197], v193 offset0:84 offset1:86
	s_nop 0
	v_cvt_pk_bf16_f32 v230, v82, v83
	v_cvt_pk_bf16_f32 v231, v84, v85
	v_cvt_pk_bf16_f32 v232, v86, v87
	v_cvt_pk_bf16_f32 v233, v88, v89
	s_waitcnt lgkmcnt(3)
	s_nop 0
	v_mfma_f32_32x32x16_bf16 v[130:145], v[218:221], v[230:233], v[130:145]
	ds_read2_b64 v[218:221], v193 offset0:88 offset1:90
	s_nop 0
	v_cvt_pk_bf16_f32 v230, v90, v91
	v_cvt_pk_bf16_f32 v231, v92, v93
	v_cvt_pk_bf16_f32 v232, v94, v95
	v_cvt_pk_bf16_f32 v233, v96, v97
	s_waitcnt lgkmcnt(3)
	s_nop 0
	v_mfma_f32_32x32x16_bf16 v[130:145], v[222:225], v[230:233], v[130:145]
	ds_read2_b64 v[222:225], v193 offset0:92 offset1:94
	s_nop 0
	v_cvt_pk_bf16_f32 v230, v98, v99
	v_cvt_pk_bf16_f32 v231, v100, v101
	v_cvt_pk_bf16_f32 v232, v102, v103
	v_cvt_pk_bf16_f32 v233, v104, v105
	s_waitcnt lgkmcnt(3)
	s_nop 0
	v_mfma_f32_32x32x16_bf16 v[130:145], v[226:229], v[230:233], v[130:145]
	s_nop 0
	v_cvt_pk_bf16_f32 v226, v106, v107
	v_cvt_pk_bf16_f32 v227, v108, v109
	v_cvt_pk_bf16_f32 v228, v110, v111
	v_cvt_pk_bf16_f32 v229, v112, v113
	s_waitcnt lgkmcnt(2)
	s_nop 0
	v_mfma_f32_32x32x16_bf16 v[130:145], v[194:197], v[226:229], v[130:145]
	s_nop 0
	v_cvt_pk_bf16_f32 v194, v114, v115
	v_cvt_pk_bf16_f32 v195, v116, v117
	v_cvt_pk_bf16_f32 v196, v118, v119
	v_cvt_pk_bf16_f32 v197, v120, v121
	s_waitcnt lgkmcnt(1)
	s_nop 0
	v_mfma_f32_32x32x16_bf16 v[130:145], v[218:221], v[194:197], v[130:145]
	s_nop 0
	v_cvt_pk_bf16_f32 v194, v122, v123
	v_cvt_pk_bf16_f32 v195, v124, v125
	v_cvt_pk_bf16_f32 v196, v126, v127
	v_cvt_pk_bf16_f32 v197, v128, v129
	s_waitcnt lgkmcnt(0)
	s_nop 0
	v_mfma_f32_32x32x16_bf16 v[130:145], v[222:225], v[194:197], v[130:145]
	v_fmamk_f32 v193, v192, 0x42000000, v153
	v_exp_f32_e32 v193, v193
	v_or_b32_e32 v194, 0x20000, v172
	v_mov_b32_e32 v195, v173
	v_lshl_add_u64 v[194:195], v[170:171], 0, v[194:195]
	s_nop 6
	v_mul_f32_e32 v130, v193, v130
	v_cvt_pk_bf16_f32 v130, v130, s0
	global_store_short v[194:195], v130, off
	v_fmamk_f32 v130, v192, 0x42040000, v153
	v_exp_f32_e32 v130, v130
	s_nop 0
	v_mul_f32_e32 v130, v130, v131
	v_cvt_pk_bf16_f32 v193, v130, s0
	v_or_b32_e32 v130, 0x21000, v172
	v_mov_b32_e32 v131, v173
	v_lshl_add_u64 v[130:131], v[170:171], 0, v[130:131]
	global_store_short v[130:131], v193, off
	v_fmamk_f32 v130, v192, 0x42080000, v153
	v_exp_f32_e32 v130, v130
	v_mov_b32_e32 v131, v173
	v_mul_f32_e32 v130, v130, v132
	v_cvt_pk_bf16_f32 v132, v130, s0
	v_or_b32_e32 v130, 0x22000, v172
	v_lshl_add_u64 v[130:131], v[170:171], 0, v[130:131]
	global_store_short v[130:131], v132, off
	v_fmamk_f32 v130, v192, 0x420c0000, v153
	v_exp_f32_e32 v130, v130
	v_mov_b32_e32 v131, v173
	v_mul_f32_e32 v130, v130, v133
	v_cvt_pk_bf16_f32 v132, v130, s0
	v_or_b32_e32 v130, 0x23000, v172
	v_lshl_add_u64 v[130:131], v[170:171], 0, v[130:131]
	global_store_short v[130:131], v132, off
	v_fmamk_f32 v130, v192, 0x42200000, v153
	v_exp_f32_e32 v130, v130
	v_mov_b32_e32 v131, v173
	v_mul_f32_e32 v130, v130, v134
	v_cvt_pk_bf16_f32 v132, v130, s0
	v_or_b32_e32 v130, 0x28000, v172
	v_lshl_add_u64 v[130:131], v[170:171], 0, v[130:131]
	global_store_short v[130:131], v132, off
	v_fmamk_f32 v130, v192, 0x42240000, v153
	v_exp_f32_e32 v130, v130
	v_mov_b32_e32 v131, v173
	v_mul_f32_e32 v130, v130, v135
	v_cvt_pk_bf16_f32 v132, v130, s0
	v_or_b32_e32 v130, 0x29000, v172
	v_lshl_add_u64 v[130:131], v[170:171], 0, v[130:131]
	global_store_short v[130:131], v132, off
	v_fmamk_f32 v130, v192, 0x42280000, v153
	v_exp_f32_e32 v130, v130
	v_mov_b32_e32 v131, v173
	v_mul_f32_e32 v130, v130, v136
	v_cvt_pk_bf16_f32 v132, v130, s0
	v_or_b32_e32 v130, 0x2a000, v172
	v_lshl_add_u64 v[130:131], v[170:171], 0, v[130:131]
	global_store_short v[130:131], v132, off
	v_fmamk_f32 v130, v192, 0x422c0000, v153
	v_exp_f32_e32 v130, v130
	v_mov_b32_e32 v131, v173
	v_mul_f32_e32 v130, v130, v137
	v_cvt_pk_bf16_f32 v132, v130, s0
	v_or_b32_e32 v130, 0x2b000, v172
	v_lshl_add_u64 v[130:131], v[170:171], 0, v[130:131]
	global_store_short v[130:131], v132, off
	v_fmamk_f32 v130, v192, 0x42400000, v153
	v_exp_f32_e32 v130, v130
	v_mov_b32_e32 v131, v173
	v_mul_f32_e32 v130, v130, v138
	v_cvt_pk_bf16_f32 v132, v130, s0
	v_or_b32_e32 v130, 0x30000, v172
	v_lshl_add_u64 v[130:131], v[170:171], 0, v[130:131]
	global_store_short v[130:131], v132, off
	v_fmamk_f32 v130, v192, 0x42440000, v153
	v_exp_f32_e32 v130, v130
	v_mov_b32_e32 v131, v173
	v_mul_f32_e32 v130, v130, v139
	v_cvt_pk_bf16_f32 v132, v130, s0
	v_or_b32_e32 v130, 0x31000, v172
	v_lshl_add_u64 v[130:131], v[170:171], 0, v[130:131]
	global_store_short v[130:131], v132, off
	v_fmamk_f32 v130, v192, 0x42480000, v153
	v_exp_f32_e32 v130, v130
	v_mov_b32_e32 v131, v173
	v_mul_f32_e32 v130, v130, v140
	v_cvt_pk_bf16_f32 v132, v130, s0
	v_or_b32_e32 v130, 0x32000, v172
	v_lshl_add_u64 v[130:131], v[170:171], 0, v[130:131]
	global_store_short v[130:131], v132, off
	v_fmamk_f32 v130, v192, 0x424c0000, v153
	v_exp_f32_e32 v130, v130
	v_mov_b32_e32 v131, v173
	v_mul_f32_e32 v130, v130, v141
	v_cvt_pk_bf16_f32 v132, v130, s0
	v_or_b32_e32 v130, 0x33000, v172
	v_lshl_add_u64 v[130:131], v[170:171], 0, v[130:131]
	global_store_short v[130:131], v132, off
	v_fmamk_f32 v130, v192, 0x42600000, v153
	v_exp_f32_e32 v130, v130
	v_mov_b32_e32 v131, v173
	v_mul_f32_e32 v130, v130, v142
	v_cvt_pk_bf16_f32 v132, v130, s0
	v_or_b32_e32 v130, 0x38000, v172
	v_lshl_add_u64 v[130:131], v[170:171], 0, v[130:131]
	global_store_short v[130:131], v132, off
	v_fmamk_f32 v130, v192, 0x42640000, v153
	v_exp_f32_e32 v130, v130
	v_mov_b32_e32 v131, v173
	v_mul_f32_e32 v130, v130, v143
	v_cvt_pk_bf16_f32 v132, v130, s0
	v_or_b32_e32 v130, 0x39000, v172
	v_lshl_add_u64 v[130:131], v[170:171], 0, v[130:131]
	global_store_short v[130:131], v132, off
	v_fmamk_f32 v130, v192, 0x42680000, v153
	v_exp_f32_e32 v130, v130
	v_mov_b32_e32 v131, v173
	v_mul_f32_e32 v130, v130, v144
	v_cvt_pk_bf16_f32 v132, v130, s0
	v_or_b32_e32 v130, 0x3a000, v172
	v_lshl_add_u64 v[130:131], v[170:171], 0, v[130:131]
	global_store_short v[130:131], v132, off
	v_fmamk_f32 v130, v192, 0x426c0000, v153
	v_exp_f32_e32 v130, v130
	v_mov_b32_e32 v131, v173
	v_mul_f32_e32 v130, v130, v145
	v_cvt_pk_bf16_f32 v132, v130, s0
	v_or_b32_e32 v130, 0x3b000, v172
	v_lshl_add_u64 v[130:131], v[170:171], 0, v[130:131]
	global_store_short v[130:131], v132, off
	v_add_u32_e32 v193, 0x8000, v178
	ds_read2_b64 v[130:133], v193 offset0:64 offset1:66
	ds_read2_b64 v[194:197], v193 offset0:68 offset1:70
	ds_read2_b64 v[218:221], v193 offset0:72 offset1:74
	ds_read2_b64 v[222:225], v193 offset0:76 offset1:78
	s_nop 0
	v_cvt_pk_bf16_f32 v134, v2, v3
	v_cvt_pk_bf16_f32 v135, v4, v5
	v_cvt_pk_bf16_f32 v136, v6, v7
	v_cvt_pk_bf16_f32 v137, v8, v9
	s_waitcnt lgkmcnt(3)
	s_nop 0
	v_mfma_f32_32x32x16_bf16 v[130:145], v[130:133], v[134:137], 0
	ds_read2_b64 v[226:229], v193 offset0:80 offset1:82
	s_nop 0
	v_cvt_pk_bf16_f32 v230, v10, v11
	v_cvt_pk_bf16_f32 v231, v12, v13
	v_cvt_pk_bf16_f32 v232, v14, v15
	v_cvt_pk_bf16_f32 v233, v16, v17
	s_waitcnt lgkmcnt(3)
	s_nop 0
	v_mfma_f32_32x32x16_bf16 v[130:145], v[194:197], v[230:233], v[130:145]
	ds_read2_b64 v[194:197], v193 offset0:84 offset1:86
	s_nop 0
	v_cvt_pk_bf16_f32 v230, v18, v19
	v_cvt_pk_bf16_f32 v231, v20, v21
	v_cvt_pk_bf16_f32 v232, v22, v23
	v_cvt_pk_bf16_f32 v233, v24, v25
	s_waitcnt lgkmcnt(3)
	s_nop 0
	v_mfma_f32_32x32x16_bf16 v[130:145], v[218:221], v[230:233], v[130:145]
	ds_read2_b64 v[218:221], v193 offset0:88 offset1:90
	s_nop 0
	v_cvt_pk_bf16_f32 v230, v26, v27
	v_cvt_pk_bf16_f32 v231, v28, v29
	v_cvt_pk_bf16_f32 v232, v30, v31
	v_cvt_pk_bf16_f32 v233, v32, v33
	s_waitcnt lgkmcnt(3)
	s_nop 0
	v_mfma_f32_32x32x16_bf16 v[130:145], v[222:225], v[230:233], v[130:145]
	ds_read2_b64 v[222:225], v193 offset0:92 offset1:94
	s_nop 0
	v_cvt_pk_bf16_f32 v230, v34, v35
	v_cvt_pk_bf16_f32 v231, v36, v37
	v_cvt_pk_bf16_f32 v232, v38, v39
	v_cvt_pk_bf16_f32 v233, v40, v41
	s_waitcnt lgkmcnt(3)
	s_nop 0
	v_mfma_f32_32x32x16_bf16 v[130:145], v[226:229], v[230:233], v[130:145]
	ds_read2_b64 v[226:229], v193 offset0:96 offset1:98
	s_nop 0
	v_cvt_pk_bf16_f32 v230, v42, v43
	v_cvt_pk_bf16_f32 v231, v44, v45
	v_cvt_pk_bf16_f32 v232, v46, v47
	v_cvt_pk_bf16_f32 v233, v48, v49
	s_waitcnt lgkmcnt(3)
	s_nop 0
	v_mfma_f32_32x32x16_bf16 v[130:145], v[194:197], v[230:233], v[130:145]
	ds_read2_b64 v[194:197], v193 offset0:100 offset1:102
	s_nop 0
	v_cvt_pk_bf16_f32 v230, v50, v51
	v_cvt_pk_bf16_f32 v231, v52, v53
	v_cvt_pk_bf16_f32 v232, v54, v55
	v_cvt_pk_bf16_f32 v233, v56, v57
	s_waitcnt lgkmcnt(3)
	s_nop 0
	v_mfma_f32_32x32x16_bf16 v[130:145], v[218:221], v[230:233], v[130:145]
	ds_read2_b64 v[218:221], v193 offset0:104 offset1:106
	s_nop 0
	v_cvt_pk_bf16_f32 v230, v58, v59
	v_cvt_pk_bf16_f32 v231, v60, v61
	v_cvt_pk_bf16_f32 v232, v62, v63
	v_cvt_pk_bf16_f32 v233, v64, v65
	s_waitcnt lgkmcnt(3)
	s_nop 0
	v_mfma_f32_32x32x16_bf16 v[130:145], v[222:225], v[230:233], v[130:145]
	ds_read2_b64 v[222:225], v193 offset0:108 offset1:110
	s_nop 0
	v_cvt_pk_bf16_f32 v230, v66, v67
	v_cvt_pk_bf16_f32 v231, v68, v69
	v_cvt_pk_bf16_f32 v232, v70, v71
	v_cvt_pk_bf16_f32 v233, v72, v73
	s_waitcnt lgkmcnt(3)
	s_nop 0
	v_mfma_f32_32x32x16_bf16 v[130:145], v[226:229], v[230:233], v[130:145]
	ds_read2_b64 v[226:229], v193 offset0:112 offset1:114
	s_nop 0
	v_cvt_pk_bf16_f32 v230, v74, v75
	v_cvt_pk_bf16_f32 v231, v76, v77
	v_cvt_pk_bf16_f32 v232, v78, v79
	v_cvt_pk_bf16_f32 v233, v80, v81
	s_waitcnt lgkmcnt(3)
	s_nop 0
	v_mfma_f32_32x32x16_bf16 v[130:145], v[194:197], v[230:233], v[130:145]
	ds_read2_b64 v[194:197], v193 offset0:116 offset1:118
	s_nop 0
	v_cvt_pk_bf16_f32 v230, v82, v83
	v_cvt_pk_bf16_f32 v231, v84, v85
	v_cvt_pk_bf16_f32 v232, v86, v87
	v_cvt_pk_bf16_f32 v233, v88, v89
	s_waitcnt lgkmcnt(3)
	s_nop 0
	v_mfma_f32_32x32x16_bf16 v[130:145], v[218:221], v[230:233], v[130:145]
	ds_read2_b64 v[218:221], v193 offset0:120 offset1:122
	s_nop 0
	v_cvt_pk_bf16_f32 v230, v90, v91
	v_cvt_pk_bf16_f32 v231, v92, v93
	v_cvt_pk_bf16_f32 v232, v94, v95
	v_cvt_pk_bf16_f32 v233, v96, v97
	s_waitcnt lgkmcnt(3)
	s_nop 0
	v_mfma_f32_32x32x16_bf16 v[130:145], v[222:225], v[230:233], v[130:145]
	ds_read2_b64 v[222:225], v193 offset0:124 offset1:126
	s_nop 0
	v_cvt_pk_bf16_f32 v230, v98, v99
	v_cvt_pk_bf16_f32 v231, v100, v101
	v_cvt_pk_bf16_f32 v232, v102, v103
	v_cvt_pk_bf16_f32 v233, v104, v105
	s_waitcnt lgkmcnt(3)
	s_nop 0
	v_mfma_f32_32x32x16_bf16 v[130:145], v[226:229], v[230:233], v[130:145]
	s_nop 0
	v_cvt_pk_bf16_f32 v226, v106, v107
	v_cvt_pk_bf16_f32 v227, v108, v109
	v_cvt_pk_bf16_f32 v228, v110, v111
	v_cvt_pk_bf16_f32 v229, v112, v113
	s_waitcnt lgkmcnt(2)
	s_nop 0
	v_mfma_f32_32x32x16_bf16 v[130:145], v[194:197], v[226:229], v[130:145]
	s_nop 0
	v_cvt_pk_bf16_f32 v194, v114, v115
	v_cvt_pk_bf16_f32 v195, v116, v117
	v_cvt_pk_bf16_f32 v196, v118, v119
	v_cvt_pk_bf16_f32 v197, v120, v121
	s_waitcnt lgkmcnt(1)
	s_nop 0
	v_mfma_f32_32x32x16_bf16 v[130:145], v[218:221], v[194:197], v[130:145]
	s_nop 0
	v_cvt_pk_bf16_f32 v194, v122, v123
	v_cvt_pk_bf16_f32 v195, v124, v125
	v_cvt_pk_bf16_f32 v196, v126, v127
	v_cvt_pk_bf16_f32 v197, v128, v129
	s_waitcnt lgkmcnt(0)
	s_nop 0
	v_mfma_f32_32x32x16_bf16 v[130:145], v[222:225], v[194:197], v[130:145]
	v_fmamk_f32 v193, v192, 0x42800000, v153
	v_exp_f32_e32 v193, v193
	v_or_b32_e32 v194, 0x40000, v172
	v_mov_b32_e32 v195, v173
	v_lshl_add_u64 v[194:195], v[170:171], 0, v[194:195]
	s_nop 6
	v_mul_f32_e32 v130, v193, v130
	v_cvt_pk_bf16_f32 v130, v130, s0
	global_store_short v[194:195], v130, off
	v_fmamk_f32 v130, v192, 0x42820000, v153
	v_exp_f32_e32 v130, v130
	s_nop 0
	v_mul_f32_e32 v130, v130, v131
	v_cvt_pk_bf16_f32 v193, v130, s0
	v_or_b32_e32 v130, 0x41000, v172
	v_mov_b32_e32 v131, v173
	v_lshl_add_u64 v[130:131], v[170:171], 0, v[130:131]
	global_store_short v[130:131], v193, off
	v_fmamk_f32 v130, v192, 0x42840000, v153
	v_exp_f32_e32 v130, v130
	v_mov_b32_e32 v131, v173
	v_mul_f32_e32 v130, v130, v132
	v_cvt_pk_bf16_f32 v132, v130, s0
	v_or_b32_e32 v130, 0x42000, v172
	v_lshl_add_u64 v[130:131], v[170:171], 0, v[130:131]
	global_store_short v[130:131], v132, off
	v_fmamk_f32 v130, v192, 0x42860000, v153
	v_exp_f32_e32 v130, v130
	v_mov_b32_e32 v131, v173
	v_mul_f32_e32 v130, v130, v133
	v_cvt_pk_bf16_f32 v132, v130, s0
	v_or_b32_e32 v130, 0x43000, v172
	v_lshl_add_u64 v[130:131], v[170:171], 0, v[130:131]
	global_store_short v[130:131], v132, off
	v_fmamk_f32 v130, v192, 0x42900000, v153
	v_exp_f32_e32 v130, v130
	v_mov_b32_e32 v131, v173
	v_mul_f32_e32 v130, v130, v134
	v_cvt_pk_bf16_f32 v132, v130, s0
	v_or_b32_e32 v130, 0x48000, v172
	v_lshl_add_u64 v[130:131], v[170:171], 0, v[130:131]
	global_store_short v[130:131], v132, off
	v_fmamk_f32 v130, v192, 0x42920000, v153
	v_exp_f32_e32 v130, v130
	v_mov_b32_e32 v131, v173
	v_mul_f32_e32 v130, v130, v135
	v_cvt_pk_bf16_f32 v132, v130, s0
	v_or_b32_e32 v130, 0x49000, v172
	v_lshl_add_u64 v[130:131], v[170:171], 0, v[130:131]
	global_store_short v[130:131], v132, off
	v_fmamk_f32 v130, v192, 0x42940000, v153
	v_exp_f32_e32 v130, v130
	v_mov_b32_e32 v131, v173
	v_mul_f32_e32 v130, v130, v136
	v_cvt_pk_bf16_f32 v132, v130, s0
	v_or_b32_e32 v130, 0x4a000, v172
	v_lshl_add_u64 v[130:131], v[170:171], 0, v[130:131]
	global_store_short v[130:131], v132, off
	v_fmamk_f32 v130, v192, 0x42960000, v153
	v_exp_f32_e32 v130, v130
	v_mov_b32_e32 v131, v173
	v_mul_f32_e32 v130, v130, v137
	v_cvt_pk_bf16_f32 v132, v130, s0
	v_or_b32_e32 v130, 0x4b000, v172
	v_lshl_add_u64 v[130:131], v[170:171], 0, v[130:131]
	global_store_short v[130:131], v132, off
	v_fmamk_f32 v130, v192, 0x42a00000, v153
	v_exp_f32_e32 v130, v130
	v_mov_b32_e32 v131, v173
	v_mul_f32_e32 v130, v130, v138
	v_cvt_pk_bf16_f32 v132, v130, s0
	v_or_b32_e32 v130, 0x50000, v172
	v_lshl_add_u64 v[130:131], v[170:171], 0, v[130:131]
	global_store_short v[130:131], v132, off
	v_fmamk_f32 v130, v192, 0x42a20000, v153
	v_exp_f32_e32 v130, v130
	v_mov_b32_e32 v131, v173
	v_mul_f32_e32 v130, v130, v139
	v_cvt_pk_bf16_f32 v132, v130, s0
	v_or_b32_e32 v130, 0x51000, v172
	v_lshl_add_u64 v[130:131], v[170:171], 0, v[130:131]
	global_store_short v[130:131], v132, off
	v_fmamk_f32 v130, v192, 0x42a40000, v153
	v_exp_f32_e32 v130, v130
	v_mov_b32_e32 v131, v173
	v_mul_f32_e32 v130, v130, v140
	v_cvt_pk_bf16_f32 v132, v130, s0
	v_or_b32_e32 v130, 0x52000, v172
	v_lshl_add_u64 v[130:131], v[170:171], 0, v[130:131]
	global_store_short v[130:131], v132, off
	v_fmamk_f32 v130, v192, 0x42a60000, v153
	v_exp_f32_e32 v130, v130
	v_mov_b32_e32 v131, v173
	v_mul_f32_e32 v130, v130, v141
	v_cvt_pk_bf16_f32 v132, v130, s0
	v_or_b32_e32 v130, 0x53000, v172
	v_lshl_add_u64 v[130:131], v[170:171], 0, v[130:131]
	global_store_short v[130:131], v132, off
	v_fmamk_f32 v130, v192, 0x42b00000, v153
	v_exp_f32_e32 v130, v130
	v_mov_b32_e32 v131, v173
	v_mul_f32_e32 v130, v130, v142
	v_cvt_pk_bf16_f32 v132, v130, s0
	v_or_b32_e32 v130, 0x58000, v172
	v_lshl_add_u64 v[130:131], v[170:171], 0, v[130:131]
	global_store_short v[130:131], v132, off
	v_fmamk_f32 v130, v192, 0x42b20000, v153
	v_exp_f32_e32 v130, v130
	v_mov_b32_e32 v131, v173
	v_mul_f32_e32 v130, v130, v143
	v_cvt_pk_bf16_f32 v132, v130, s0
	v_or_b32_e32 v130, 0x59000, v172
	v_lshl_add_u64 v[130:131], v[170:171], 0, v[130:131]
	global_store_short v[130:131], v132, off
	v_fmamk_f32 v130, v192, 0x42b40000, v153
	v_exp_f32_e32 v130, v130
	v_mov_b32_e32 v131, v173
	v_mul_f32_e32 v130, v130, v144
	v_cvt_pk_bf16_f32 v132, v130, s0
	v_or_b32_e32 v130, 0x5a000, v172
	v_lshl_add_u64 v[130:131], v[170:171], 0, v[130:131]
	global_store_short v[130:131], v132, off
	v_fmamk_f32 v130, v192, 0x42b60000, v153
	v_exp_f32_e32 v130, v130
	v_mov_b32_e32 v131, v173
	v_mul_f32_e32 v130, v130, v145
	v_cvt_pk_bf16_f32 v132, v130, s0
	v_or_b32_e32 v130, 0x5b000, v172
	v_lshl_add_u64 v[130:131], v[170:171], 0, v[130:131]
	global_store_short v[130:131], v132, off
	v_add_u32_e32 v193, 0xc000, v178
	ds_read2_b64 v[130:133], v193 offset0:96 offset1:98
	ds_read2_b64 v[194:197], v193 offset0:100 offset1:102
	ds_read2_b64 v[218:221], v193 offset0:104 offset1:106
	ds_read2_b64 v[222:225], v193 offset0:108 offset1:110
	s_nop 0
	v_cvt_pk_bf16_f32 v134, v2, v3
	v_cvt_pk_bf16_f32 v135, v4, v5
	v_cvt_pk_bf16_f32 v136, v6, v7
	v_cvt_pk_bf16_f32 v137, v8, v9
	s_waitcnt lgkmcnt(3)
	s_nop 0
	v_mfma_f32_32x32x16_bf16 v[130:145], v[130:133], v[134:137], 0
	ds_read2_b64 v[226:229], v193 offset0:112 offset1:114
	s_nop 0
	v_cvt_pk_bf16_f32 v230, v10, v11
	v_cvt_pk_bf16_f32 v231, v12, v13
	v_cvt_pk_bf16_f32 v232, v14, v15
	v_cvt_pk_bf16_f32 v233, v16, v17
	s_waitcnt lgkmcnt(3)
	s_nop 0
	v_mfma_f32_32x32x16_bf16 v[130:145], v[194:197], v[230:233], v[130:145]
	ds_read2_b64 v[194:197], v193 offset0:116 offset1:118
	s_nop 0
	v_cvt_pk_bf16_f32 v230, v18, v19
	v_cvt_pk_bf16_f32 v231, v20, v21
	v_cvt_pk_bf16_f32 v232, v22, v23
	v_cvt_pk_bf16_f32 v233, v24, v25
	s_waitcnt lgkmcnt(3)
	s_nop 0
	v_mfma_f32_32x32x16_bf16 v[130:145], v[218:221], v[230:233], v[130:145]
	ds_read2_b64 v[218:221], v193 offset0:120 offset1:122
	s_nop 0
	v_cvt_pk_bf16_f32 v230, v26, v27
	v_cvt_pk_bf16_f32 v231, v28, v29
	v_cvt_pk_bf16_f32 v232, v30, v31
	v_cvt_pk_bf16_f32 v233, v32, v33
	s_waitcnt lgkmcnt(3)
	s_nop 0
	v_mfma_f32_32x32x16_bf16 v[130:145], v[222:225], v[230:233], v[130:145]
	ds_read2_b64 v[222:225], v193 offset0:124 offset1:126
	s_nop 0
	v_cvt_pk_bf16_f32 v230, v34, v35
	v_cvt_pk_bf16_f32 v231, v36, v37
	v_cvt_pk_bf16_f32 v232, v38, v39
	v_cvt_pk_bf16_f32 v233, v40, v41
	s_waitcnt lgkmcnt(3)
	s_nop 0
	v_mfma_f32_32x32x16_bf16 v[130:145], v[226:229], v[230:233], v[130:145]
	ds_read2_b64 v[226:229], v193 offset0:128 offset1:130
	s_nop 0
	v_cvt_pk_bf16_f32 v230, v42, v43
	v_cvt_pk_bf16_f32 v231, v44, v45
	v_cvt_pk_bf16_f32 v232, v46, v47
	v_cvt_pk_bf16_f32 v233, v48, v49
	s_waitcnt lgkmcnt(3)
	s_nop 0
	v_mfma_f32_32x32x16_bf16 v[130:145], v[194:197], v[230:233], v[130:145]
	ds_read2_b64 v[194:197], v193 offset0:132 offset1:134
	s_nop 0
	v_cvt_pk_bf16_f32 v230, v50, v51
	v_cvt_pk_bf16_f32 v231, v52, v53
	v_cvt_pk_bf16_f32 v232, v54, v55
	v_cvt_pk_bf16_f32 v233, v56, v57
	s_waitcnt lgkmcnt(3)
	s_nop 0
	v_mfma_f32_32x32x16_bf16 v[130:145], v[218:221], v[230:233], v[130:145]
	ds_read2_b64 v[218:221], v193 offset0:136 offset1:138
	s_nop 0
	v_cvt_pk_bf16_f32 v230, v58, v59
	v_cvt_pk_bf16_f32 v231, v60, v61
	v_cvt_pk_bf16_f32 v232, v62, v63
	v_cvt_pk_bf16_f32 v233, v64, v65
	s_waitcnt lgkmcnt(3)
	s_nop 0
	v_mfma_f32_32x32x16_bf16 v[130:145], v[222:225], v[230:233], v[130:145]
	ds_read2_b64 v[222:225], v193 offset0:140 offset1:142
	s_nop 0
	v_cvt_pk_bf16_f32 v230, v66, v67
	v_cvt_pk_bf16_f32 v231, v68, v69
	v_cvt_pk_bf16_f32 v232, v70, v71
	v_cvt_pk_bf16_f32 v233, v72, v73
	s_waitcnt lgkmcnt(3)
	s_nop 0
	v_mfma_f32_32x32x16_bf16 v[130:145], v[226:229], v[230:233], v[130:145]
	ds_read2_b64 v[226:229], v193 offset0:144 offset1:146
	s_nop 0
	v_cvt_pk_bf16_f32 v230, v74, v75
	v_cvt_pk_bf16_f32 v231, v76, v77
	v_cvt_pk_bf16_f32 v232, v78, v79
	v_cvt_pk_bf16_f32 v233, v80, v81
	s_waitcnt lgkmcnt(3)
	s_nop 0
	v_mfma_f32_32x32x16_bf16 v[130:145], v[194:197], v[230:233], v[130:145]
	ds_read2_b64 v[194:197], v193 offset0:148 offset1:150
	s_nop 0
	v_cvt_pk_bf16_f32 v230, v82, v83
	v_cvt_pk_bf16_f32 v231, v84, v85
	v_cvt_pk_bf16_f32 v232, v86, v87
	v_cvt_pk_bf16_f32 v233, v88, v89
	s_waitcnt lgkmcnt(3)
	s_nop 0
	v_mfma_f32_32x32x16_bf16 v[130:145], v[218:221], v[230:233], v[130:145]
	ds_read2_b64 v[218:221], v193 offset0:152 offset1:154
	s_nop 0
	v_cvt_pk_bf16_f32 v230, v90, v91
	v_cvt_pk_bf16_f32 v231, v92, v93
	v_cvt_pk_bf16_f32 v232, v94, v95
	v_cvt_pk_bf16_f32 v233, v96, v97
	s_waitcnt lgkmcnt(3)
	s_nop 0
	v_mfma_f32_32x32x16_bf16 v[130:145], v[222:225], v[230:233], v[130:145]
	ds_read2_b64 v[222:225], v193 offset0:156 offset1:158
	s_nop 0
	v_cvt_pk_bf16_f32 v230, v98, v99
	v_cvt_pk_bf16_f32 v231, v100, v101
	v_cvt_pk_bf16_f32 v232, v102, v103
	v_cvt_pk_bf16_f32 v233, v104, v105
	s_waitcnt lgkmcnt(3)
	s_nop 0
	v_mfma_f32_32x32x16_bf16 v[130:145], v[226:229], v[230:233], v[130:145]
	s_nop 0
	v_cvt_pk_bf16_f32 v226, v106, v107
	v_cvt_pk_bf16_f32 v227, v108, v109
	v_cvt_pk_bf16_f32 v228, v110, v111
	v_cvt_pk_bf16_f32 v229, v112, v113
	s_waitcnt lgkmcnt(2)
	s_nop 0
	v_mfma_f32_32x32x16_bf16 v[130:145], v[194:197], v[226:229], v[130:145]
	s_nop 0
	v_cvt_pk_bf16_f32 v194, v114, v115
	v_cvt_pk_bf16_f32 v195, v116, v117
	v_cvt_pk_bf16_f32 v196, v118, v119
	v_cvt_pk_bf16_f32 v197, v120, v121
	s_waitcnt lgkmcnt(1)
	s_nop 0
	v_mfma_f32_32x32x16_bf16 v[130:145], v[218:221], v[194:197], v[130:145]
	s_nop 0
	v_cvt_pk_bf16_f32 v194, v122, v123
	v_cvt_pk_bf16_f32 v195, v124, v125
	v_cvt_pk_bf16_f32 v196, v126, v127
	v_cvt_pk_bf16_f32 v197, v128, v129
	s_waitcnt lgkmcnt(0)
	s_nop 0
	v_mfma_f32_32x32x16_bf16 v[130:145], v[222:225], v[194:197], v[130:145]
	v_fmamk_f32 v193, v192, 0x42c00000, v153
	v_exp_f32_e32 v193, v193
	v_or_b32_e32 v194, 0x60000, v172
	v_mov_b32_e32 v195, v173
	v_lshl_add_u64 v[194:195], v[170:171], 0, v[194:195]
	s_nop 6
	v_mul_f32_e32 v130, v193, v130
	v_cvt_pk_bf16_f32 v130, v130, s0
	global_store_short v[194:195], v130, off
	v_fmamk_f32 v130, v192, 0x42c20000, v153
	v_exp_f32_e32 v130, v130
	s_nop 0
	v_mul_f32_e32 v130, v130, v131
	v_cvt_pk_bf16_f32 v193, v130, s0
	v_or_b32_e32 v130, 0x61000, v172
	v_mov_b32_e32 v131, v173
	v_lshl_add_u64 v[130:131], v[170:171], 0, v[130:131]
	global_store_short v[130:131], v193, off
	v_fmamk_f32 v130, v192, 0x42c40000, v153
	v_exp_f32_e32 v130, v130
	v_mov_b32_e32 v131, v173
	v_mul_f32_e32 v130, v130, v132
	v_cvt_pk_bf16_f32 v132, v130, s0
	v_or_b32_e32 v130, 0x62000, v172
	v_lshl_add_u64 v[130:131], v[170:171], 0, v[130:131]
	global_store_short v[130:131], v132, off
	v_fmamk_f32 v130, v192, 0x42c60000, v153
	v_exp_f32_e32 v130, v130
	v_mov_b32_e32 v131, v173
	v_mul_f32_e32 v130, v130, v133
	v_cvt_pk_bf16_f32 v132, v130, s0
	v_or_b32_e32 v130, 0x63000, v172
	v_lshl_add_u64 v[130:131], v[170:171], 0, v[130:131]
	global_store_short v[130:131], v132, off
	v_fmamk_f32 v130, v192, 0x42d00000, v153
	v_exp_f32_e32 v130, v130
	v_mov_b32_e32 v131, v173
	v_mul_f32_e32 v130, v130, v134
	v_cvt_pk_bf16_f32 v132, v130, s0
	v_or_b32_e32 v130, 0x68000, v172
	v_lshl_add_u64 v[130:131], v[170:171], 0, v[130:131]
	global_store_short v[130:131], v132, off
	v_fmamk_f32 v130, v192, 0x42d20000, v153
	v_exp_f32_e32 v130, v130
	v_mov_b32_e32 v131, v173
	v_mul_f32_e32 v130, v130, v135
	v_cvt_pk_bf16_f32 v132, v130, s0
	v_or_b32_e32 v130, 0x69000, v172
	v_lshl_add_u64 v[130:131], v[170:171], 0, v[130:131]
	global_store_short v[130:131], v132, off
	v_fmamk_f32 v130, v192, 0x42d40000, v153
	v_exp_f32_e32 v130, v130
	v_mov_b32_e32 v131, v173
	v_mul_f32_e32 v130, v130, v136
	v_cvt_pk_bf16_f32 v132, v130, s0
	v_or_b32_e32 v130, 0x6a000, v172
	v_lshl_add_u64 v[130:131], v[170:171], 0, v[130:131]
	global_store_short v[130:131], v132, off
	v_fmamk_f32 v130, v192, 0x42d60000, v153
	v_exp_f32_e32 v130, v130
	v_mov_b32_e32 v131, v173
	v_mul_f32_e32 v130, v130, v137
	v_cvt_pk_bf16_f32 v132, v130, s0
	v_or_b32_e32 v130, 0x6b000, v172
	v_lshl_add_u64 v[130:131], v[170:171], 0, v[130:131]
	global_store_short v[130:131], v132, off
	v_fmamk_f32 v130, v192, 0x42e00000, v153
	v_exp_f32_e32 v130, v130
	v_mov_b32_e32 v131, v173
	v_mul_f32_e32 v130, v130, v138
	v_cvt_pk_bf16_f32 v132, v130, s0
	v_or_b32_e32 v130, 0x70000, v172
	v_lshl_add_u64 v[130:131], v[170:171], 0, v[130:131]
	global_store_short v[130:131], v132, off
	v_fmamk_f32 v130, v192, 0x42e20000, v153
	v_exp_f32_e32 v130, v130
	v_mov_b32_e32 v131, v173
	v_mul_f32_e32 v130, v130, v139
	v_cvt_pk_bf16_f32 v132, v130, s0
	v_or_b32_e32 v130, 0x71000, v172
	v_lshl_add_u64 v[130:131], v[170:171], 0, v[130:131]
	global_store_short v[130:131], v132, off
	v_fmamk_f32 v130, v192, 0x42e40000, v153
	v_exp_f32_e32 v130, v130
	v_mov_b32_e32 v131, v173
	v_mul_f32_e32 v130, v130, v140
	v_cvt_pk_bf16_f32 v132, v130, s0
	v_or_b32_e32 v130, 0x72000, v172
	v_lshl_add_u64 v[130:131], v[170:171], 0, v[130:131]
	global_store_short v[130:131], v132, off
	v_fmamk_f32 v130, v192, 0x42e60000, v153
	v_exp_f32_e32 v130, v130
	v_mov_b32_e32 v131, v173
	v_mul_f32_e32 v130, v130, v141
	v_cvt_pk_bf16_f32 v132, v130, s0
	v_or_b32_e32 v130, 0x73000, v172
	v_lshl_add_u64 v[130:131], v[170:171], 0, v[130:131]
	global_store_short v[130:131], v132, off
	v_fmamk_f32 v130, v192, 0x42f00000, v153
	v_exp_f32_e32 v130, v130
	v_mov_b32_e32 v131, v173
	v_mul_f32_e32 v130, v130, v142
	v_cvt_pk_bf16_f32 v132, v130, s0
	v_or_b32_e32 v130, 0x78000, v172
	v_lshl_add_u64 v[130:131], v[170:171], 0, v[130:131]
	global_store_short v[130:131], v132, off
	v_fmamk_f32 v130, v192, 0x42f20000, v153
	v_exp_f32_e32 v130, v130
	v_mov_b32_e32 v131, v173
	v_mul_f32_e32 v130, v130, v143
	v_cvt_pk_bf16_f32 v132, v130, s0
	v_or_b32_e32 v130, 0x79000, v172
	v_lshl_add_u64 v[130:131], v[170:171], 0, v[130:131]
	global_store_short v[130:131], v132, off
	v_fmamk_f32 v130, v192, 0x42f40000, v153
	v_exp_f32_e32 v130, v130
	v_mov_b32_e32 v131, v173
	v_fmac_f32_e32 v153, 0x42f60000, v192
	v_mul_f32_e32 v130, v130, v144
	v_cvt_pk_bf16_f32 v132, v130, s0
	v_or_b32_e32 v130, 0x7a000, v172
	v_lshl_add_u64 v[130:131], v[170:171], 0, v[130:131]
	global_store_short v[130:131], v132, off
	v_exp_f32_e32 v130, v153
	v_or_b32_e32 v172, 0x7b000, v172
	v_mul_f32_e32 v130, v130, v145
	v_cvt_pk_bf16_f32 v132, v130, s0
	v_lshl_add_u64 v[130:131], v[170:171], 0, v[172:173]
	global_store_short v[130:131], v132, off
	v_mov_b32_e32 v153, v189
	s_waitcnt vmcnt(63) expcnt(7) lgkmcnt(15)
	s_barrier
	v_lshl_add_u64 v[132:133], s[64:65], 0, v[164:165]
	v_lshlrev_b64 v[130:131], 1, v[168:169]
	v_lshl_add_u64 v[132:133], v[132:133], 0, v[130:131]
	v_lshlrev_b32_e32 v134, 4, v153
	v_and_b32_e32 v144, 0xf0, v134
	v_mov_b32_e32 v145, v1
	v_lshlrev_b32_e32 v134, 10, v153
	v_lshl_add_u64 v[132:133], v[132:133], 0, v[144:145]
	v_and_b32_e32 v134, 0x3c000, v134
	v_mov_b32_e32 v135, v1
	v_lshl_add_u64 v[172:173], v[132:133], 0, v[134:135]
	s_mov_b32 s6, 0xe640000
	v_add_co_u32_e64 v132, s[6:7], s6, v172
	v_bfe_u32 v145, v153, 4, 4
	s_nop 0
	v_addc_co_u32_e64 v133, s[6:7], 0, v173, s[6:7]
	s_mov_b32 s6, 0xe680000
	s_nop 0
	v_add_co_u32_e64 v136, s[6:7], s6, v172
	global_load_dwordx4 v[132:135], v[132:133], off
	s_nop 0
	v_addc_co_u32_e64 v137, s[6:7], 0, v173, s[6:7]
	s_mov_b32 s6, 0xe6c0000
	s_nop 0
	v_add_co_u32_e64 v140, s[6:7], s6, v172
	global_load_dwordx4 v[136:139], v[136:137], off
	s_nop 0
	v_addc_co_u32_e64 v141, s[6:7], 0, v173, s[6:7]
	s_mov_b32 s6, 0xe700000
	s_nop 0
	v_add_co_u32_e64 v168, s[6:7], s6, v172
	global_load_dwordx4 v[140:143], v[140:141], off
	s_nop 0
	v_addc_co_u32_e64 v169, s[6:7], 0, v173, s[6:7]
	s_mov_b32 s6, 0xe740000
	s_nop 0
	v_add_co_u32_e64 v192, s[6:7], s6, v172
	global_load_dwordx4 v[168:171], v[168:169], off
	s_nop 0
	v_addc_co_u32_e64 v193, s[6:7], 0, v173, s[6:7]
	s_mov_b32 s6, 0xe780000
	s_nop 0
	v_add_co_u32_e64 v196, s[6:7], s6, v172
	global_load_dwordx4 v[192:195], v[192:193], off
	s_nop 0
	v_addc_co_u32_e64 v197, s[6:7], 0, v173, s[6:7]
	s_mov_b32 s6, 0xe7c0000
	s_nop 0
	v_add_co_u32_e64 v208, s[6:7], s6, v172
	global_load_dwordx4 v[196:199], v[196:197], off
	s_nop 0
	v_addc_co_u32_e64 v209, s[6:7], 0, v173, s[6:7]
	s_mov_b32 s6, 0xe800000
	global_load_dwordx4 v[218:221], v[208:209], off
	v_add_co_u32_e64 v208, s[6:7], s6, v172
	v_mul_u32_u24_e32 v145, 0x108, v145
	s_nop 0
	v_addc_co_u32_e64 v209, s[6:7], 0, v173, s[6:7]
	global_load_dwordx4 v[222:225], v[208:209], off
	v_add3_u32 v153, v149, v144, v145
	s_waitcnt vmcnt(7)
	ds_write2_b64 v153, v[132:133], v[134:135] offset1:1
	v_add_u32_e32 v132, 0x1080, v153
	s_waitcnt vmcnt(6)
	ds_write2_b64 v132, v[136:137], v[138:139] offset1:1
	v_add_u32_e32 v132, 0x2100, v153
	s_waitcnt vmcnt(5)
	ds_write2_b64 v132, v[140:141], v[142:143] offset1:1
	v_add_u32_e32 v132, 0x3180, v153
	s_waitcnt vmcnt(4)
	ds_write2_b64 v132, v[168:169], v[170:171] offset1:1
	v_add_u32_e32 v132, 0x4200, v153
	s_waitcnt vmcnt(3)
	ds_write2_b64 v132, v[192:193], v[194:195] offset1:1
	v_add_u32_e32 v132, 0x5280, v153
	s_waitcnt vmcnt(2)
	ds_write2_b64 v132, v[196:197], v[198:199] offset1:1
	v_add_u32_e32 v132, 0x6300, v153
	s_waitcnt vmcnt(1)
	ds_write2_b64 v132, v[218:219], v[220:221] offset1:1
	v_add_u32_e32 v132, 0x7380, v153
	s_waitcnt vmcnt(0)
	ds_write2_b64 v132, v[222:223], v[224:225] offset1:1
	s_mov_b32 s6, 0xe840000
	v_add_co_u32_e64 v132, s[6:7], s6, v172
	s_nop 1
	v_addc_co_u32_e64 v133, s[6:7], 0, v173, s[6:7]
	s_mov_b32 s6, 0xe880000
	s_nop 0
	v_add_co_u32_e64 v136, s[6:7], s6, v172
	global_load_dwordx4 v[132:135], v[132:133], off
	s_nop 0
	v_addc_co_u32_e64 v137, s[6:7], 0, v173, s[6:7]
	s_mov_b32 s6, 0xe8c0000
	s_nop 0
	v_add_co_u32_e64 v140, s[6:7], s6, v172
	global_load_dwordx4 v[136:139], v[136:137], off
	s_nop 0
	v_addc_co_u32_e64 v141, s[6:7], 0, v173, s[6:7]
	s_mov_b32 s6, 0xe900000
	s_nop 0
	v_add_co_u32_e64 v144, s[6:7], s6, v172
	global_load_dwordx4 v[140:143], v[140:141], off
	s_nop 0
	v_addc_co_u32_e64 v145, s[6:7], 0, v173, s[6:7]
	s_mov_b32 s6, 0xe940000
	global_load_dwordx4 v[168:171], v[144:145], off
	v_add_co_u32_e64 v144, s[6:7], s6, v172
	s_nop 1
	v_addc_co_u32_e64 v145, s[6:7], 0, v173, s[6:7]
	s_mov_b32 s6, 0xe980000
	global_load_dwordx4 v[192:195], v[144:145], off
	v_add_co_u32_e64 v144, s[6:7], s6, v172
	s_nop 1
	v_addc_co_u32_e64 v145, s[6:7], 0, v173, s[6:7]
	s_mov_b32 s6, 0xe9c0000
	global_load_dwordx4 v[196:199], v[144:145], off
	v_add_co_u32_e64 v144, s[6:7], s6, v172
	s_nop 1
	v_addc_co_u32_e64 v145, s[6:7], 0, v173, s[6:7]
	s_mov_b32 s6, 0xea00000
	global_load_dwordx4 v[218:221], v[144:145], off
	v_add_co_u32_e64 v144, s[6:7], s6, v172
	s_nop 1
	v_addc_co_u32_e64 v145, s[6:7], 0, v173, s[6:7]
	global_load_dwordx4 v[222:225], v[144:145], off
	v_add_u32_e32 v144, 0x8400, v153
	s_waitcnt vmcnt(7)
	ds_write2_b64 v144, v[132:133], v[134:135] offset1:1
	v_add_u32_e32 v132, 0x9480, v153
	s_waitcnt vmcnt(6)
	ds_write2_b64 v132, v[136:137], v[138:139] offset1:1
	v_add_u32_e32 v132, 0xa500, v153
	s_waitcnt vmcnt(5)
	ds_write2_b64 v132, v[140:141], v[142:143] offset1:1
	v_add_u32_e32 v132, 0xb580, v153
	s_waitcnt vmcnt(4)
	ds_write2_b64 v132, v[168:169], v[170:171] offset1:1
	v_add_u32_e32 v132, 0xc600, v153
	s_waitcnt vmcnt(3)
	ds_write2_b64 v132, v[192:193], v[194:195] offset1:1
	v_add_u32_e32 v132, 0xd680, v153
	s_waitcnt vmcnt(2)
	ds_write2_b64 v132, v[196:197], v[198:199] offset1:1
	v_add_u32_e32 v132, 0xe700, v153
	s_waitcnt vmcnt(1)
	ds_write2_b64 v132, v[218:219], v[220:221] offset1:1
	v_add_u32_e32 v132, 0xf780, v153
	s_waitcnt vmcnt(0)
	ds_write2_b64 v132, v[222:223], v[224:225] offset1:1
	s_waitcnt lgkmcnt(0)
	s_barrier
	v_lshlrev_b64 v[132:133], 14, v[166:167]
	v_lshl_add_u64 v[132:133], s[64:65], 0, v[132:133]
	v_lshl_add_u64 v[130:131], v[132:133], 0, v[130:131]
	v_mov_b32_e32 v153, v1
	v_lshl_add_u64 v[134:135], v[130:131], 0, v[152:153]
	s_mov_b32 s6, 0xf640000
	v_add_co_u32_e64 v130, s[6:7], s6, v134
	v_mul_f32 v2, v2, v159
	v_mul_f32 v3, v3, v159
	v_mul_f32 v4, v4, v159
	v_mul_f32 v5, v5, v159
	s_nop 1
	v_addc_co_u32_e64 v131, s[6:7], 0, v135, s[6:7]
	v_mul_f32 v6, v6, v159
	v_mul_f32 v7, v7, v159
	v_mul_f32 v8, v8, v159
	v_mul_f32 v9, v9, v159
	v_mul_f32 v10, v10, v159
	v_mul_f32 v11, v11, v159
	v_mul_f32 v12, v12, v159
	v_mul_f32 v13, v13, v159
	v_mul_f32 v14, v14, v159
	v_mul_f32 v15, v15, v159
	v_mul_f32 v16, v16, v159
	v_mul_f32 v17, v17, v159
	v_mul_f32 v18, v18, v159
	v_mul_f32 v19, v19, v159
	v_mul_f32 v20, v20, v159
	v_mul_f32 v21, v21, v159
	v_mul_f32 v22, v22, v159
	v_mul_f32 v23, v23, v159
	v_mul_f32 v24, v24, v159
	v_mul_f32 v25, v25, v159
	v_mul_f32 v26, v26, v159
	v_mul_f32 v27, v27, v159
	v_mul_f32 v28, v28, v159
	v_mul_f32 v29, v29, v159
	v_mul_f32 v30, v30, v159
	v_mul_f32 v31, v31, v159
	v_mul_f32 v32, v32, v159
	v_mul_f32 v33, v33, v159
	v_mul_f32 v34, v34, v159
	v_mul_f32 v35, v35, v159
	v_mul_f32 v36, v36, v159
	v_mul_f32 v37, v37, v159
	v_mul_f32 v38, v38, v159
	v_mul_f32 v39, v39, v159
	v_mul_f32 v40, v40, v159
	v_mul_f32 v41, v41, v159
	v_mul_f32 v42, v42, v159
	v_mul_f32 v43, v43, v159
	v_mul_f32 v44, v44, v159
	v_mul_f32 v45, v45, v159
	v_mul_f32 v46, v46, v159
	v_mul_f32 v47, v47, v159
	v_mul_f32 v48, v48, v159
	v_mul_f32 v49, v49, v159
	v_mul_f32 v50, v50, v159
	v_mul_f32 v51, v51, v159
	v_mul_f32 v52, v52, v159
	v_mul_f32 v53, v53, v159
	v_mul_f32 v54, v54, v159
	v_mul_f32 v55, v55, v159
	v_mul_f32 v56, v56, v159
	v_mul_f32 v57, v57, v159
	v_mul_f32 v58, v58, v159
	v_mul_f32 v59, v59, v159
	v_mul_f32 v60, v60, v159
	v_mul_f32 v61, v61, v159
	v_mul_f32 v62, v62, v159
	v_mul_f32 v63, v63, v159
	v_mul_f32 v64, v64, v159
	v_mul_f32 v65, v65, v159
	v_mul_f32 v66, v66, v159
	v_mul_f32 v67, v67, v159
	v_mul_f32 v68, v68, v159
	v_mul_f32 v69, v69, v159
	v_mul_f32 v70, v70, v159
	v_mul_f32 v71, v71, v159
	v_mul_f32 v72, v72, v159
	v_mul_f32 v73, v73, v159
	v_mul_f32 v74, v74, v159
	v_mul_f32 v75, v75, v159
	v_mul_f32 v76, v76, v159
	v_mul_f32 v77, v77, v159
	v_mul_f32 v78, v78, v159
	v_mul_f32 v79, v79, v159
	v_mul_f32 v80, v80, v159
	v_mul_f32 v81, v81, v159
	v_mul_f32 v82, v82, v159
	v_mul_f32 v83, v83, v159
	v_mul_f32 v84, v84, v159
	v_mul_f32 v85, v85, v159
	v_mul_f32 v86, v86, v159
	v_mul_f32 v87, v87, v159
	v_mul_f32 v88, v88, v159
	v_mul_f32 v89, v89, v159
	v_mul_f32 v90, v90, v159
	v_mul_f32 v91, v91, v159
	v_mul_f32 v92, v92, v159
	v_mul_f32 v93, v93, v159
	v_mul_f32 v94, v94, v159
	v_mul_f32 v95, v95, v159
	v_mul_f32 v96, v96, v159
	v_mul_f32 v97, v97, v159
	v_mul_f32 v98, v98, v159
	v_mul_f32 v99, v99, v159
	v_mul_f32 v100, v100, v159
	v_mul_f32 v101, v101, v159
	v_mul_f32 v102, v102, v159
	v_mul_f32 v103, v103, v159
	v_mul_f32 v104, v104, v159
	v_mul_f32 v105, v105, v159
	v_mul_f32 v106, v106, v159
	v_mul_f32 v107, v107, v159
	v_mul_f32 v108, v108, v159
	v_mul_f32 v109, v109, v159
	v_mul_f32 v110, v110, v159
	v_mul_f32 v111, v111, v159
	v_mul_f32 v112, v112, v159
	v_mul_f32 v113, v113, v159
	v_mul_f32 v114, v114, v159
	v_mul_f32 v115, v115, v159
	v_mul_f32 v116, v116, v159
	v_mul_f32 v117, v117, v159
	v_mul_f32 v118, v118, v159
	v_mul_f32 v119, v119, v159
	v_mul_f32 v120, v120, v159
	v_mul_f32 v121, v121, v159
	v_mul_f32 v122, v122, v159
	v_mul_f32 v123, v123, v159
	v_mul_f32 v124, v124, v159
	v_mul_f32 v125, v125, v159
	v_mul_f32 v126, v126, v159
	v_mul_f32 v127, v127, v159
	v_mul_f32 v128, v128, v159
	v_mul_f32 v129, v129, v159
	global_load_dwordx4 v[130:133], v[130:131], off
	s_mov_b64 s[6:7], 0xf640000
	v_lshl_add_u64 v[142:143], v[134:135], 0, s[6:7]
	global_load_dwordx4 v[134:137], v[142:143], off offset:32
	global_load_dwordx4 v[138:141], v[142:143], off offset:64
	global_load_dwordx4 v[166:169], v[142:143], off offset:96
	global_load_dwordx4 v[234:237], v[142:143], off offset:128
	global_load_dwordx4 v[238:241], v[142:143], off offset:160
	global_load_dwordx4 v[242:245], v[142:143], off offset:192
	global_load_dwordx4 v[246:249], v[142:143], off offset:224
	v_fma_f32 v144, 0, v191, v190
	v_add_f32_e32 v145, v190, v191
	v_exp_f32_e32 v144, v144
	v_exp_f32_e32 v145, v145
	v_fmamk_f32 v153, v191, 0x42480000, v190
	s_waitcnt vmcnt(7)
	v_lshlrev_b32_e32 v170, 16, v130
	v_and_b32_e32 v171, 0xffff0000, v130
	v_fma_f32 v130, 2.0, v191, v190
	v_pk_mul_f32 v[144:145], v[144:145], v[170:171]
	v_exp_f32_e32 v170, v130
	v_fmamk_f32 v130, v191, 0x40400000, v190
	v_exp_f32_e32 v171, v130
	v_cvt_pk_bf16_f32 v130, v144, v145
	v_lshlrev_b32_e32 v144, 16, v131
	v_and_b32_e32 v145, 0xffff0000, v131
	v_fma_f32 v131, 4.0, v191, v190
	v_pk_mul_f32 v[144:145], v[170:171], v[144:145]
	v_exp_f32_e32 v170, v131
	v_fmamk_f32 v131, v191, 0x40a00000, v190
	v_exp_f32_e32 v171, v131
	v_cvt_pk_bf16_f32 v131, v144, v145
	v_lshlrev_b32_e32 v144, 16, v132
	v_and_b32_e32 v145, 0xffff0000, v132
	v_fmamk_f32 v132, v191, 0x40c00000, v190
	v_pk_mul_f32 v[144:145], v[170:171], v[144:145]
	v_exp_f32_e32 v170, v132
	v_fmamk_f32 v132, v191, 0x40e00000, v190
	v_exp_f32_e32 v171, v132
	v_cvt_pk_bf16_f32 v132, v144, v145
	v_lshlrev_b32_e32 v144, 16, v133
	v_and_b32_e32 v145, 0xffff0000, v133
	v_fmamk_f32 v133, v191, 0x41800000, v190
	v_pk_mul_f32 v[144:145], v[170:171], v[144:145]
	v_exp_f32_e32 v170, v133
	v_fmamk_f32 v133, v191, 0x41880000, v190
	v_exp_f32_e32 v171, v133
	v_cvt_pk_bf16_f32 v133, v144, v145
	s_waitcnt vmcnt(6)
	v_lshlrev_b32_e32 v144, 16, v134
	v_and_b32_e32 v145, 0xffff0000, v134
	v_fmamk_f32 v134, v191, 0x41900000, v190
	v_pk_mul_f32 v[144:145], v[170:171], v[144:145]
	v_exp_f32_e32 v170, v134
	v_fmamk_f32 v134, v191, 0x41980000, v190
	v_exp_f32_e32 v171, v134
	v_cvt_pk_bf16_f32 v134, v144, v145
	v_lshlrev_b32_e32 v144, 16, v135
	v_and_b32_e32 v145, 0xffff0000, v135
	v_fmamk_f32 v135, v191, 0x41a00000, v190
	v_pk_mul_f32 v[144:145], v[170:171], v[144:145]
	v_exp_f32_e32 v170, v135
	v_fmamk_f32 v135, v191, 0x41a80000, v190
	v_exp_f32_e32 v171, v135
	v_cvt_pk_bf16_f32 v135, v144, v145
	v_lshlrev_b32_e32 v144, 16, v136
	v_and_b32_e32 v145, 0xffff0000, v136
	v_fmamk_f32 v136, v191, 0x41b00000, v190
	v_pk_mul_f32 v[144:145], v[170:171], v[144:145]
	v_exp_f32_e32 v170, v136
	v_fmamk_f32 v136, v191, 0x41b80000, v190
	v_exp_f32_e32 v171, v136
	v_cvt_pk_bf16_f32 v136, v144, v145
	v_lshlrev_b32_e32 v144, 16, v137
	v_and_b32_e32 v145, 0xffff0000, v137
	v_fmamk_f32 v137, v191, 0x42000000, v190
	v_pk_mul_f32 v[144:145], v[170:171], v[144:145]
	v_exp_f32_e32 v170, v137
	v_fmamk_f32 v137, v191, 0x42040000, v190
	v_exp_f32_e32 v171, v137
	v_cvt_pk_bf16_f32 v137, v144, v145
	s_waitcnt vmcnt(5)
	v_lshlrev_b32_e32 v144, 16, v138
	v_and_b32_e32 v145, 0xffff0000, v138
	v_fmamk_f32 v138, v191, 0x42080000, v190
	v_pk_mul_f32 v[144:145], v[170:171], v[144:145]
	v_exp_f32_e32 v170, v138
	v_fmamk_f32 v138, v191, 0x420c0000, v190
	v_exp_f32_e32 v171, v138
	v_cvt_pk_bf16_f32 v138, v144, v145
	v_lshlrev_b32_e32 v144, 16, v139
	v_and_b32_e32 v145, 0xffff0000, v139
	v_fmamk_f32 v139, v191, 0x42100000, v190
	v_pk_mul_f32 v[144:145], v[170:171], v[144:145]
	v_exp_f32_e32 v170, v139
	v_fmamk_f32 v139, v191, 0x42140000, v190
	v_exp_f32_e32 v171, v139
	v_cvt_pk_bf16_f32 v139, v144, v145
	v_lshlrev_b32_e32 v144, 16, v140
	v_and_b32_e32 v145, 0xffff0000, v140
	v_fmamk_f32 v140, v191, 0x42180000, v190
	v_pk_mul_f32 v[144:145], v[170:171], v[144:145]
	v_exp_f32_e32 v170, v140
	v_fmamk_f32 v140, v191, 0x421c0000, v190
	v_exp_f32_e32 v171, v140
	v_cvt_pk_bf16_f32 v140, v144, v145
	v_lshlrev_b32_e32 v144, 16, v141
	v_and_b32_e32 v145, 0xffff0000, v141
	v_fmamk_f32 v141, v191, 0x42400000, v190
	v_pk_mul_f32 v[144:145], v[170:171], v[144:145]
	v_exp_f32_e32 v170, v141
	v_fmamk_f32 v141, v191, 0x42440000, v190
	v_exp_f32_e32 v171, v141
	v_cvt_pk_bf16_f32 v141, v144, v145
	s_waitcnt vmcnt(4)
	v_lshlrev_b32_e32 v144, 16, v166
	v_and_b32_e32 v145, 0xffff0000, v166
	v_pk_mul_f32 v[144:145], v[170:171], v[144:145]
	v_exp_f32_e32 v170, v153
	v_fmamk_f32 v153, v191, 0x424c0000, v190
	v_exp_f32_e32 v171, v153
	v_cvt_pk_bf16_f32 v166, v144, v145
	v_lshlrev_b32_e32 v144, 16, v167
	v_and_b32_e32 v145, 0xffff0000, v167
	v_fmamk_f32 v153, v191, 0x42500000, v190
	v_pk_mul_f32 v[144:145], v[170:171], v[144:145]
	v_exp_f32_e32 v170, v153
	v_fmamk_f32 v153, v191, 0x42540000, v190
	v_exp_f32_e32 v171, v153
	v_cvt_pk_bf16_f32 v167, v144, v145
	v_lshlrev_b32_e32 v144, 16, v168
	v_and_b32_e32 v145, 0xffff0000, v168
	v_fmamk_f32 v153, v191, 0x42580000, v190
	v_pk_mul_f32 v[144:145], v[170:171], v[144:145]
	v_exp_f32_e32 v170, v153
	v_fmamk_f32 v153, v191, 0x425c0000, v190
	v_exp_f32_e32 v171, v153
	v_cvt_pk_bf16_f32 v168, v144, v145
	v_lshlrev_b32_e32 v144, 16, v169
	v_and_b32_e32 v145, 0xffff0000, v169
	v_pk_mul_f32 v[144:145], v[170:171], v[144:145]
	s_nop 0
	v_cvt_pk_bf16_f32 v169, v144, v145
	ds_read2_b64 v[170:173], v179 offset1:1
	ds_read2_b64 v[192:195], v179 offset0:4 offset1:5
	ds_read2_b64 v[196:199], v179 offset0:8 offset1:9
	ds_read2_b64 v[218:221], v179 offset0:12 offset1:13
	s_waitcnt lgkmcnt(3)
	v_mfma_f32_32x32x16_bf16 v[2:17], v[170:173], v[130:133], v[2:17]
	v_add_u32_e32 v144, 0x2100, v179
	ds_read2_b64 v[170:173], v144 offset1:1
	s_waitcnt lgkmcnt(3)
	v_mfma_f32_32x32x16_bf16 v[2:17], v[192:195], v[134:137], v[2:17]
	v_add_u32_e32 v144, 0x2120, v179
	ds_read2_b64 v[192:195], v144 offset1:1
	s_waitcnt lgkmcnt(3)
	v_mfma_f32_32x32x16_bf16 v[2:17], v[196:199], v[138:141], v[2:17]
	v_add_u32_e32 v144, 0x2140, v179
	ds_read2_b64 v[196:199], v144 offset1:1
	s_waitcnt lgkmcnt(3)
	v_mfma_f32_32x32x16_bf16 v[2:17], v[218:221], v[166:169], v[2:17]
	v_add_u32_e32 v144, 0x2160, v179
	ds_read2_b64 v[218:221], v144 offset1:1
	s_waitcnt lgkmcnt(3)
	v_mfma_f32_32x32x16_bf16 v[18:33], v[170:173], v[130:133], v[18:33]
	v_add_u32_e32 v144, 0x4200, v179
	ds_read2_b64 v[170:173], v144 offset1:1
	s_waitcnt lgkmcnt(3)
	v_mfma_f32_32x32x16_bf16 v[18:33], v[192:195], v[134:137], v[18:33]
	v_add_u32_e32 v144, 0x4220, v179
	ds_read2_b64 v[192:195], v144 offset1:1
	s_waitcnt lgkmcnt(3)
	v_mfma_f32_32x32x16_bf16 v[18:33], v[196:199], v[138:141], v[18:33]
	v_add_u32_e32 v144, 0x4240, v179
	ds_read2_b64 v[196:199], v144 offset1:1
	s_waitcnt lgkmcnt(3)
	v_mfma_f32_32x32x16_bf16 v[18:33], v[218:221], v[166:169], v[18:33]
	v_add_u32_e32 v144, 0x4260, v179
	ds_read2_b64 v[218:221], v144 offset1:1
	s_waitcnt lgkmcnt(3)
	v_mfma_f32_32x32x16_bf16 v[34:49], v[170:173], v[130:133], v[34:49]
	v_add_u32_e32 v144, 0x6300, v179
	ds_read2_b64 v[170:173], v144 offset1:1
	s_waitcnt lgkmcnt(3)
	v_mfma_f32_32x32x16_bf16 v[34:49], v[192:195], v[134:137], v[34:49]
	v_add_u32_e32 v144, 0x6320, v179
	ds_read2_b64 v[192:195], v144 offset1:1
	s_waitcnt lgkmcnt(3)
	v_mfma_f32_32x32x16_bf16 v[34:49], v[196:199], v[138:141], v[34:49]
	v_add_u32_e32 v144, 0x6340, v179
	ds_read2_b64 v[196:199], v144 offset1:1
	s_waitcnt lgkmcnt(3)
	v_mfma_f32_32x32x16_bf16 v[34:49], v[218:221], v[166:169], v[34:49]
	v_add_u32_e32 v144, 0x6360, v179
	ds_read2_b64 v[218:221], v144 offset1:1
	s_waitcnt lgkmcnt(3)
	v_mfma_f32_32x32x16_bf16 v[50:65], v[170:173], v[130:133], v[50:65]
	v_add_u32_e32 v144, 0x8400, v179
	ds_read2_b64 v[170:173], v144 offset1:1
	s_waitcnt lgkmcnt(3)
	v_mfma_f32_32x32x16_bf16 v[50:65], v[192:195], v[134:137], v[50:65]
	v_add_u32_e32 v144, 0x8420, v179
	ds_read2_b64 v[192:195], v144 offset1:1
	s_waitcnt lgkmcnt(3)
	v_mfma_f32_32x32x16_bf16 v[50:65], v[196:199], v[138:141], v[50:65]
	v_add_u32_e32 v144, 0x8440, v179
	ds_read2_b64 v[196:199], v144 offset1:1
	s_waitcnt lgkmcnt(3)
	v_mfma_f32_32x32x16_bf16 v[50:65], v[218:221], v[166:169], v[50:65]
	v_add_u32_e32 v144, 0x8460, v179
	ds_read2_b64 v[218:221], v144 offset1:1
	s_waitcnt lgkmcnt(3)
	v_mfma_f32_32x32x16_bf16 v[66:81], v[170:173], v[130:133], v[66:81]
	v_add_u32_e32 v144, 0xa500, v179
	ds_read2_b64 v[170:173], v144 offset1:1
	s_waitcnt lgkmcnt(3)
	v_mfma_f32_32x32x16_bf16 v[66:81], v[192:195], v[134:137], v[66:81]
	v_add_u32_e32 v144, 0xa520, v179
	ds_read2_b64 v[192:195], v144 offset1:1
	s_waitcnt lgkmcnt(3)
	v_mfma_f32_32x32x16_bf16 v[66:81], v[196:199], v[138:141], v[66:81]
	v_add_u32_e32 v144, 0xa540, v179
	ds_read2_b64 v[196:199], v144 offset1:1
	s_waitcnt lgkmcnt(3)
	v_mfma_f32_32x32x16_bf16 v[66:81], v[218:221], v[166:169], v[66:81]
	v_add_u32_e32 v144, 0xa560, v179
	ds_read2_b64 v[218:221], v144 offset1:1
	s_waitcnt lgkmcnt(3)
	v_mfma_f32_32x32x16_bf16 v[82:97], v[170:173], v[130:133], v[82:97]
	v_add_u32_e32 v144, 0xc600, v179
	ds_read2_b64 v[170:173], v144 offset1:1
	s_waitcnt lgkmcnt(3)
	v_mfma_f32_32x32x16_bf16 v[82:97], v[192:195], v[134:137], v[82:97]
	v_add_u32_e32 v144, 0xc620, v179
	ds_read2_b64 v[192:195], v144 offset1:1
	s_waitcnt lgkmcnt(3)
	v_mfma_f32_32x32x16_bf16 v[82:97], v[196:199], v[138:141], v[82:97]
	v_add_u32_e32 v144, 0xc640, v179
	ds_read2_b64 v[196:199], v144 offset1:1
	s_waitcnt lgkmcnt(3)
	v_mfma_f32_32x32x16_bf16 v[82:97], v[218:221], v[166:169], v[82:97]
	v_add_u32_e32 v144, 0xc660, v179
	ds_read2_b64 v[218:221], v144 offset1:1
	s_waitcnt lgkmcnt(3)
	v_mfma_f32_32x32x16_bf16 v[98:113], v[170:173], v[130:133], v[98:113]
	v_add_u32_e32 v144, 0xe700, v179
	ds_read2_b64 v[170:173], v144 offset1:1
	s_waitcnt lgkmcnt(3)
	v_mfma_f32_32x32x16_bf16 v[98:113], v[192:195], v[134:137], v[98:113]
	v_add_u32_e32 v144, 0xe720, v179
	ds_read2_b64 v[192:195], v144 offset1:1
	s_waitcnt lgkmcnt(3)
	v_mfma_f32_32x32x16_bf16 v[98:113], v[196:199], v[138:141], v[98:113]
	v_add_u32_e32 v144, 0xe740, v179
	ds_read2_b64 v[196:199], v144 offset1:1
	s_waitcnt lgkmcnt(3)
	v_mfma_f32_32x32x16_bf16 v[98:113], v[218:221], v[166:169], v[98:113]
	v_add_u32_e32 v144, 0xe760, v179
	ds_read2_b64 v[218:221], v144 offset1:1
	s_waitcnt lgkmcnt(3)
	v_mfma_f32_32x32x16_bf16 v[114:129], v[170:173], v[130:133], v[114:129]
	s_waitcnt lgkmcnt(2)
	v_mfma_f32_32x32x16_bf16 v[114:129], v[192:195], v[134:137], v[114:129]
	s_waitcnt lgkmcnt(1)
	v_mfma_f32_32x32x16_bf16 v[114:129], v[196:199], v[138:141], v[114:129]
	s_waitcnt lgkmcnt(0)
	v_mfma_f32_32x32x16_bf16 v[114:129], v[218:221], v[166:169], v[114:129]
	v_fmamk_f32 v134, v191, 0x42800000, v190
	v_fmamk_f32 v135, v191, 0x42820000, v190
	v_exp_f32_e32 v134, v134
	v_exp_f32_e32 v135, v135
	v_fmamk_f32 v138, v191, 0x42a00000, v190
	v_fmamk_f32 v139, v191, 0x42a20000, v190
	v_exp_f32_e32 v138, v138
	v_exp_f32_e32 v139, v139
	v_fmamk_f32 v144, v191, 0x42c00000, v190
	v_fmamk_f32 v145, v191, 0x42c20000, v190
	v_exp_f32_e32 v144, v144
	v_exp_f32_e32 v145, v145
	v_fmamk_f32 v153, v191, 0x42e00000, v190
	s_waitcnt vmcnt(0)
	v_mov_b32_e32 v130, v234
	v_mov_b32_e32 v131, v235
	v_mov_b32_e32 v132, v236
	v_mov_b32_e32 v133, v237
	v_lshlrev_b32_e32 v136, 16, v130
	v_and_b32_e32 v137, 0xffff0000, v130
	v_pk_mul_f32 v[134:135], v[134:135], v[136:137]
	v_lshlrev_b32_e32 v136, 16, v131
	v_cvt_pk_bf16_f32 v130, v134, v135
	v_fmamk_f32 v134, v191, 0x42840000, v190
	v_fmamk_f32 v135, v191, 0x42860000, v190
	v_exp_f32_e32 v134, v134
	v_exp_f32_e32 v135, v135
	v_and_b32_e32 v137, 0xffff0000, v131
	v_pk_mul_f32 v[134:135], v[134:135], v[136:137]
	s_nop 0
	v_cvt_pk_bf16_f32 v131, v134, v135
	v_fmamk_f32 v134, v191, 0x42880000, v190
	v_fmamk_f32 v135, v191, 0x428a0000, v190
	v_exp_f32_e32 v134, v134
	v_exp_f32_e32 v135, v135
	v_lshlrev_b32_e32 v136, 16, v132
	v_and_b32_e32 v137, 0xffff0000, v132
	v_pk_mul_f32 v[134:135], v[134:135], v[136:137]
	s_nop 0
	v_cvt_pk_bf16_f32 v132, v134, v135
	v_fmamk_f32 v134, v191, 0x428c0000, v190
	v_fmamk_f32 v135, v191, 0x428e0000, v190
	v_exp_f32_e32 v134, v134
	v_exp_f32_e32 v135, v135
	v_lshlrev_b32_e32 v136, 16, v133
	v_and_b32_e32 v137, 0xffff0000, v133
	v_pk_mul_f32 v[134:135], v[134:135], v[136:137]
	s_nop 0
	v_cvt_pk_bf16_f32 v133, v134, v135
	s_waitcnt vmcnt(0)
	v_mov_b32_e32 v134, v238
	v_mov_b32_e32 v135, v239
	v_mov_b32_e32 v136, v240
	v_mov_b32_e32 v137, v241
	v_lshlrev_b32_e32 v140, 16, v134
	v_and_b32_e32 v141, 0xffff0000, v134
	v_pk_mul_f32 v[138:139], v[138:139], v[140:141]
	v_lshlrev_b32_e32 v140, 16, v135
	v_cvt_pk_bf16_f32 v134, v138, v139
	v_fmamk_f32 v138, v191, 0x42a40000, v190
	v_fmamk_f32 v139, v191, 0x42a60000, v190
	v_exp_f32_e32 v138, v138
	v_exp_f32_e32 v139, v139
	v_and_b32_e32 v141, 0xffff0000, v135
	v_pk_mul_f32 v[138:139], v[138:139], v[140:141]
	s_nop 0
	v_cvt_pk_bf16_f32 v135, v138, v139
	v_fmamk_f32 v138, v191, 0x42a80000, v190
	v_fmamk_f32 v139, v191, 0x42aa0000, v190
	v_exp_f32_e32 v138, v138
	v_exp_f32_e32 v139, v139
	v_lshlrev_b32_e32 v140, 16, v136
	v_and_b32_e32 v141, 0xffff0000, v136
	v_pk_mul_f32 v[138:139], v[138:139], v[140:141]
	s_nop 0
	v_cvt_pk_bf16_f32 v136, v138, v139
	v_fmamk_f32 v138, v191, 0x42ac0000, v190
	v_fmamk_f32 v139, v191, 0x42ae0000, v190
	v_exp_f32_e32 v138, v138
	v_exp_f32_e32 v139, v139
	v_lshlrev_b32_e32 v140, 16, v137
	v_and_b32_e32 v141, 0xffff0000, v137
	v_pk_mul_f32 v[138:139], v[138:139], v[140:141]
	s_nop 0
	v_cvt_pk_bf16_f32 v137, v138, v139
	s_waitcnt vmcnt(0)
	v_mov_b32_e32 v138, v242
	v_mov_b32_e32 v139, v243
	v_mov_b32_e32 v140, v244
	v_mov_b32_e32 v141, v245
	v_lshlrev_b32_e32 v166, 16, v138
	v_and_b32_e32 v167, 0xffff0000, v138
	v_pk_mul_f32 v[144:145], v[144:145], v[166:167]
	v_lshlrev_b32_e32 v166, 16, v139
	v_cvt_pk_bf16_f32 v138, v144, v145
	v_fmamk_f32 v144, v191, 0x42c40000, v190
	v_fmamk_f32 v145, v191, 0x42c60000, v190
	v_exp_f32_e32 v144, v144
	v_exp_f32_e32 v145, v145
	v_and_b32_e32 v167, 0xffff0000, v139
	v_pk_mul_f32 v[144:145], v[144:145], v[166:167]
	s_nop 0
	v_cvt_pk_bf16_f32 v139, v144, v145
	v_fmamk_f32 v144, v191, 0x42c80000, v190
	v_fmamk_f32 v145, v191, 0x42ca0000, v190
	v_exp_f32_e32 v144, v144
	v_exp_f32_e32 v145, v145
	v_lshlrev_b32_e32 v166, 16, v140
	v_and_b32_e32 v167, 0xffff0000, v140
	v_pk_mul_f32 v[144:145], v[144:145], v[166:167]
	s_nop 0
	v_cvt_pk_bf16_f32 v140, v144, v145
	v_fmamk_f32 v144, v191, 0x42cc0000, v190
	v_fmamk_f32 v145, v191, 0x42ce0000, v190
	v_exp_f32_e32 v144, v144
	v_exp_f32_e32 v145, v145
	v_lshlrev_b32_e32 v166, 16, v141
	v_and_b32_e32 v167, 0xffff0000, v141
	v_pk_mul_f32 v[144:145], v[144:145], v[166:167]
	s_nop 0
	v_cvt_pk_bf16_f32 v141, v144, v145
	v_exp_f32_e32 v166, v153
	v_fmamk_f32 v153, v191, 0x42e20000, v190
	v_exp_f32_e32 v167, v153
	v_fmamk_f32 v153, v191, 0x42e40000, v190
	s_waitcnt vmcnt(0)
	v_mov_b32_e32 v142, v246
	v_mov_b32_e32 v143, v247
	v_mov_b32_e32 v144, v248
	v_mov_b32_e32 v145, v249
	v_lshlrev_b32_e32 v168, 16, v142
	v_and_b32_e32 v169, 0xffff0000, v142
	v_pk_mul_f32 v[166:167], v[166:167], v[168:169]
	v_lshlrev_b32_e32 v168, 16, v143
	v_cvt_pk_bf16_f32 v142, v166, v167
	v_exp_f32_e32 v166, v153
	v_fmamk_f32 v153, v191, 0x42e60000, v190
	v_exp_f32_e32 v167, v153
	v_and_b32_e32 v169, 0xffff0000, v143
	v_fmamk_f32 v153, v191, 0x42e80000, v190
	v_pk_mul_f32 v[166:167], v[166:167], v[168:169]
	s_nop 0
	v_cvt_pk_bf16_f32 v143, v166, v167
	v_exp_f32_e32 v166, v153
	v_fmamk_f32 v153, v191, 0x42ea0000, v190
	v_exp_f32_e32 v167, v153
	v_lshlrev_b32_e32 v168, 16, v144
	v_and_b32_e32 v169, 0xffff0000, v144
	v_fmamk_f32 v153, v191, 0x42ec0000, v190
	v_pk_mul_f32 v[166:167], v[166:167], v[168:169]
	v_fmac_f32_e32 v190, 0x42ee0000, v191
	v_cvt_pk_bf16_f32 v144, v166, v167
	v_exp_f32_e32 v166, v153
	v_exp_f32_e32 v167, v190
	v_lshlrev_b32_e32 v168, 16, v145
	v_and_b32_e32 v169, 0xffff0000, v145
	v_pk_mul_f32 v[166:167], v[166:167], v[168:169]
	s_nop 0
	v_cvt_pk_bf16_f32 v145, v166, v167
	ds_read2_b64 v[166:169], v179 offset0:16 offset1:17
	ds_read2_b64 v[170:173], v179 offset0:20 offset1:21
	ds_read2_b64 v[190:193], v179 offset0:24 offset1:25
	ds_read2_b64 v[194:197], v179 offset0:28 offset1:29
	s_waitcnt lgkmcnt(3)
	v_mfma_f32_32x32x16_bf16 v[2:17], v[166:169], v[130:133], v[2:17]
	v_add_u32_e32 v153, 0x2180, v179
	ds_read2_b64 v[166:169], v153 offset1:1
	s_waitcnt lgkmcnt(3)
	v_mfma_f32_32x32x16_bf16 v[2:17], v[170:173], v[134:137], v[2:17]
	v_add_u32_e32 v153, 0x21a0, v179
	ds_read2_b64 v[170:173], v153 offset1:1
	s_waitcnt lgkmcnt(3)
	v_mfma_f32_32x32x16_bf16 v[2:17], v[190:193], v[138:141], v[2:17]
	v_add_u32_e32 v153, 0x21c0, v179
	ds_read2_b64 v[190:193], v153 offset1:1
	s_waitcnt lgkmcnt(3)
	v_mfma_f32_32x32x16_bf16 v[2:17], v[194:197], v[142:145], v[2:17]
	v_add_u32_e32 v153, 0x21e0, v179
	ds_read2_b64 v[194:197], v153 offset1:1
	s_waitcnt lgkmcnt(3)
	v_mfma_f32_32x32x16_bf16 v[18:33], v[166:169], v[130:133], v[18:33]
	v_add_u32_e32 v153, 0x4280, v179
	ds_read2_b64 v[166:169], v153 offset1:1
	s_waitcnt lgkmcnt(3)
	v_mfma_f32_32x32x16_bf16 v[18:33], v[170:173], v[134:137], v[18:33]
	v_add_u32_e32 v153, 0x42a0, v179
	ds_read2_b64 v[170:173], v153 offset1:1
	s_waitcnt lgkmcnt(3)
	v_mfma_f32_32x32x16_bf16 v[18:33], v[190:193], v[138:141], v[18:33]
	v_add_u32_e32 v153, 0x42c0, v179
	ds_read2_b64 v[190:193], v153 offset1:1
	s_waitcnt lgkmcnt(3)
	v_mfma_f32_32x32x16_bf16 v[18:33], v[194:197], v[142:145], v[18:33]
	v_add_u32_e32 v153, 0x42e0, v179
	ds_read2_b64 v[194:197], v153 offset1:1
	s_waitcnt lgkmcnt(3)
	v_mfma_f32_32x32x16_bf16 v[34:49], v[166:169], v[130:133], v[34:49]
	v_add_u32_e32 v153, 0x6380, v179
	ds_read2_b64 v[166:169], v153 offset1:1
	s_waitcnt lgkmcnt(3)
	v_mfma_f32_32x32x16_bf16 v[34:49], v[170:173], v[134:137], v[34:49]
	v_add_u32_e32 v153, 0x63a0, v179
	ds_read2_b64 v[170:173], v153 offset1:1
	s_waitcnt lgkmcnt(3)
	v_mfma_f32_32x32x16_bf16 v[34:49], v[190:193], v[138:141], v[34:49]
	v_add_u32_e32 v153, 0x63c0, v179
	ds_read2_b64 v[190:193], v153 offset1:1
	s_waitcnt lgkmcnt(3)
	v_mfma_f32_32x32x16_bf16 v[34:49], v[194:197], v[142:145], v[34:49]
	v_add_u32_e32 v153, 0x63e0, v179
	ds_read2_b64 v[194:197], v153 offset1:1
	s_waitcnt lgkmcnt(3)
	v_mfma_f32_32x32x16_bf16 v[50:65], v[166:169], v[130:133], v[50:65]
	v_add_u32_e32 v153, 0x8480, v179
	ds_read2_b64 v[166:169], v153 offset1:1
	s_waitcnt lgkmcnt(3)
	v_mfma_f32_32x32x16_bf16 v[50:65], v[170:173], v[134:137], v[50:65]
	v_add_u32_e32 v153, 0x84a0, v179
	ds_read2_b64 v[170:173], v153 offset1:1
	s_waitcnt lgkmcnt(3)
	v_mfma_f32_32x32x16_bf16 v[50:65], v[190:193], v[138:141], v[50:65]
	v_add_u32_e32 v153, 0x84c0, v179
	ds_read2_b64 v[190:193], v153 offset1:1
	s_waitcnt lgkmcnt(3)
	v_mfma_f32_32x32x16_bf16 v[50:65], v[194:197], v[142:145], v[50:65]
	v_add_u32_e32 v153, 0x84e0, v179
	ds_read2_b64 v[194:197], v153 offset1:1
	s_waitcnt lgkmcnt(3)
	v_mfma_f32_32x32x16_bf16 v[66:81], v[166:169], v[130:133], v[66:81]
	v_add_u32_e32 v153, 0xa580, v179
	ds_read2_b64 v[166:169], v153 offset1:1
	s_waitcnt lgkmcnt(3)
	v_mfma_f32_32x32x16_bf16 v[66:81], v[170:173], v[134:137], v[66:81]
	v_add_u32_e32 v153, 0xa5a0, v179
	ds_read2_b64 v[170:173], v153 offset1:1
	s_waitcnt lgkmcnt(3)
	v_mfma_f32_32x32x16_bf16 v[66:81], v[190:193], v[138:141], v[66:81]
	v_add_u32_e32 v153, 0xa5c0, v179
	ds_read2_b64 v[190:193], v153 offset1:1
	s_waitcnt lgkmcnt(3)
	v_mfma_f32_32x32x16_bf16 v[66:81], v[194:197], v[142:145], v[66:81]
	v_add_u32_e32 v153, 0xa5e0, v179
	ds_read2_b64 v[194:197], v153 offset1:1
	s_waitcnt lgkmcnt(3)
	v_mfma_f32_32x32x16_bf16 v[82:97], v[166:169], v[130:133], v[82:97]
	v_add_u32_e32 v153, 0xc680, v179
	ds_read2_b64 v[166:169], v153 offset1:1
	s_waitcnt lgkmcnt(3)
	v_mfma_f32_32x32x16_bf16 v[82:97], v[170:173], v[134:137], v[82:97]
	v_add_u32_e32 v153, 0xc6a0, v179
	ds_read2_b64 v[170:173], v153 offset1:1
	s_waitcnt lgkmcnt(3)
	v_mfma_f32_32x32x16_bf16 v[82:97], v[190:193], v[138:141], v[82:97]
	v_add_u32_e32 v153, 0xc6c0, v179
	ds_read2_b64 v[190:193], v153 offset1:1
	s_waitcnt lgkmcnt(3)
	v_mfma_f32_32x32x16_bf16 v[82:97], v[194:197], v[142:145], v[82:97]
	v_add_u32_e32 v153, 0xc6e0, v179
	ds_read2_b64 v[194:197], v153 offset1:1
	s_waitcnt lgkmcnt(3)
	v_mfma_f32_32x32x16_bf16 v[98:113], v[166:169], v[130:133], v[98:113]
	v_add_u32_e32 v153, 0xe780, v179
	ds_read2_b64 v[166:169], v153 offset1:1
	s_waitcnt lgkmcnt(3)
	v_mfma_f32_32x32x16_bf16 v[98:113], v[170:173], v[134:137], v[98:113]
	v_add_u32_e32 v153, 0xe7a0, v179
	ds_read2_b64 v[170:173], v153 offset1:1
	s_waitcnt lgkmcnt(3)
	v_mfma_f32_32x32x16_bf16 v[98:113], v[190:193], v[138:141], v[98:113]
	v_add_u32_e32 v153, 0xe7c0, v179
	ds_read2_b64 v[190:193], v153 offset1:1
	s_waitcnt lgkmcnt(3)
	v_mfma_f32_32x32x16_bf16 v[98:113], v[194:197], v[142:145], v[98:113]
	v_add_u32_e32 v153, 0xe7e0, v179
	ds_read2_b64 v[194:197], v153 offset1:1
	s_waitcnt lgkmcnt(3)
	v_mfma_f32_32x32x16_bf16 v[114:129], v[166:169], v[130:133], v[114:129]
	s_waitcnt lgkmcnt(2)
	v_mfma_f32_32x32x16_bf16 v[114:129], v[170:173], v[134:137], v[114:129]
	s_waitcnt lgkmcnt(1)
	v_mfma_f32_32x32x16_bf16 v[114:129], v[190:193], v[138:141], v[114:129]
	s_waitcnt lgkmcnt(0)
	v_mfma_f32_32x32x16_bf16 v[114:129], v[194:197], v[142:145], v[114:129]
	s_add_i32 s66, s66, 1
	s_add_i32 s67, s67, -1
	s_cmp_eq_u32 s67, -1
	s_cbranch_scc0 .LBB0_327
	s_and_b64 vcc, exec, s[4:5]
	s_mov_b64 s[4:5], -1
	s_cbranch_vccnz .LBB0_330
	s_mov_b64 s[4:5], 0
